# SSM gelu epilogue: tanh via the exp/rcp formula (1-2/(1+exp(2|u|))) for all |u| instead of the two-path library tanhf
# speedup vs baseline: 1.0082x; 1.0082x over previous
.LBB0_485:
	s_lshl_b32 s2, s18, 4
	s_ashr_i32 s3, s2, 31
	v_ashrrev_i32_e32 v138, 2, v144
	s_lshl_b64 s[4:5], s[2:3], 2
	v_lshrrev_b32_e32 v0, 1, v144
	v_and_b32_e32 v138, 0xffffffc0, v138
	s_add_u32 s4, s28, s4
	v_and_b32_e32 v147, 8, v0
	v_add_u32_e32 v138, s8, v138
	s_addc_u32 s5, s58, s5
	v_lshlrev_b32_e32 v38, 2, v147
	v_and_or_b32 v142, v144, 15, v138
	s_barrier
	global_load_dwordx4 v[26:29], v38, s[4:5] offset:16
	s_nop 0
	global_load_dwordx4 v[38:41], v38, s[4:5]
	v_and_b32_e32 v146, 0x78, v0
	v_ashrrev_i32_e32 v143, 31, v142
	v_lshlrev_b64 v[138:139], 9, v[142:143]
	v_lshl_add_u64 v[138:139], s[0:1], 0, v[138:139]
	v_lshlrev_b32_e32 v0, 1, v146
	v_lshl_add_u64 v[144:145], v[138:139], 0, v[0:1]
	global_load_dwordx4 v[138:141], v[144:145], off
	s_mov_b32 s11, 0x3f200000
	s_waitcnt vmcnt(0)
	v_lshlrev_b32_e32 v143, 16, v138
	v_fma_f32 v134, v38, v143, v134
	v_mul_f32_e32 v143, 0x3d372713, v134
	v_mul_f32_e32 v143, v134, v143
	v_fma_f32 v143, v134, v143, v134
	v_mul_f32_e32 v143, 0x3f4c422a, v143
	s_mov_b32 s70, 0x800000
	s_mov_b32 s50, 0x8000
	s_movk_i32 s55, 0xff
	s_mov_b32 s51, 0x40000
	s_movk_i32 s48, 0x1200
	s_movk_i32 s49, 0x3000
	s_movk_i32 s56, 0x4000
	s_mov_b32 s57, 0x27fff
	s_movk_i32 s65, 0x400
	s_brev_b32 s10, -2
	s_mov_b64 s[52:53], 0x800
	v_mul_f32_e64 v148, |v143|, s76
	v_add_f32_e32 v148, v148, v148
	v_exp_f32_e32 v148, v148
	s_nop 0
	v_add_f32_e32 v148, 1.0, v148
	v_rcp_f32_e32 v148, v148
	s_nop 0
	v_fma_f32 v148, v148, -2.0, 1.0
	v_lshlrev_b32_e32 v149, 16, v140
	v_fma_f32 v130, v26, v149, v130
	v_mul_f32_e32 v149, 0x3d372713, v130
	v_mul_f32_e32 v149, v130, v149
	v_fma_f32 v149, v130, v149, v130
	v_mul_f32_e32 v149, 0x3f4c422a, v149
	v_mul_f32_e64 v150, |v149|, s76
	v_add_f32_e32 v150, v150, v150
	v_exp_f32_e32 v150, v150
	s_nop 0
	v_add_f32_e32 v150, 1.0, v150
	v_rcp_f32_e32 v150, v150
	s_nop 0
	v_fma_f32 v150, v150, -2.0, 1.0
	v_and_b32_e32 v138, 0xffff0000, v138
	v_fma_f32 v138, v39, v138, v135
	v_mul_f32_e32 v135, 0x3d372713, v138
	v_mul_f32_e32 v135, v138, v135
	v_fma_f32 v135, v138, v135, v138
	v_mul_f32_e32 v135, 0x3f4c422a, v135
	v_mul_f32_e64 v151, |v135|, s76
	v_add_f32_e32 v151, v151, v151
	v_exp_f32_e32 v151, v151
	s_nop 0
	v_add_f32_e32 v151, 1.0, v151
	v_rcp_f32_e32 v151, v151
	s_nop 0
	v_fma_f32 v151, v151, -2.0, 1.0
	v_and_b32_e32 v140, 0xffff0000, v140
	v_fma_f32 v140, v27, v140, v131
	v_mul_f32_e32 v131, 0x3d372713, v140
	v_mul_f32_e32 v131, v140, v131
	v_fma_f32 v131, v140, v131, v140
	v_mul_f32_e32 v131, 0x3f4c422a, v131
	v_mul_f32_e64 v152, |v131|, s76
	v_add_f32_e32 v152, v152, v152
	v_exp_f32_e32 v152, v152
	s_nop 0
	v_add_f32_e32 v152, 1.0, v152
	v_rcp_f32_e32 v152, v152
	s_nop 0
	v_fma_f32 v152, v152, -2.0, 1.0
	v_lshlrev_b32_e32 v153, 16, v139
	v_fma_f32 v136, v40, v153, v136
	v_mul_f32_e32 v153, 0x3d372713, v136
	v_mul_f32_e32 v153, v136, v153
	v_fma_f32 v153, v136, v153, v136
	v_mul_f32_e32 v153, 0x3f4c422a, v153
	v_mul_f32_e64 v154, |v153|, s76
	v_add_f32_e32 v154, v154, v154
	v_exp_f32_e32 v154, v154
	s_nop 0
	v_add_f32_e32 v154, 1.0, v154
	v_rcp_f32_e32 v154, v154
	s_nop 0
	v_fma_f32 v154, v154, -2.0, 1.0
	v_lshlrev_b32_e32 v155, 16, v141
	v_fma_f32 v132, v28, v155, v132
	v_mul_f32_e32 v155, 0x3d372713, v132
	v_mul_f32_e32 v155, v132, v155
	v_fma_f32 v155, v132, v155, v132
	v_mul_f32_e32 v155, 0x3f4c422a, v155
	v_mul_f32_e64 v157, |v155|, s76
	v_add_f32_e32 v157, v157, v157
	v_exp_f32_e32 v157, v157
	s_nop 0
	v_add_f32_e32 v157, 1.0, v157
	v_rcp_f32_e32 v157, v157
	s_nop 0
	v_fma_f32 v157, v157, -2.0, 1.0
	v_and_b32_e32 v139, 0xffff0000, v139
	v_fmac_f32_e32 v137, v41, v139
	v_mul_f32_e32 v139, 0x3d372713, v137
	v_mul_f32_e32 v139, v137, v139
	v_fma_f32 v139, v137, v139, v137
	v_mul_f32_e32 v139, 0x3f4c422a, v139
	v_mul_f32_e64 v158, |v139|, s76
	v_add_f32_e32 v158, v158, v158
	v_exp_f32_e32 v158, v158
	s_nop 0
	v_add_f32_e32 v158, 1.0, v158
	v_rcp_f32_e32 v158, v158
	s_nop 0
	v_fma_f32 v158, v158, -2.0, 1.0
	v_and_b32_e32 v141, 0xffff0000, v141
	v_fmac_f32_e32 v133, v29, v141
	v_mul_f32_e32 v141, 0x3d372713, v133
	v_mul_f32_e32 v141, v133, v141
	v_fma_f32 v141, v133, v141, v133
	v_mul_f32_e32 v141, 0x3f4c422a, v141
	v_mul_f32_e64 v159, |v141|, s76
	v_add_f32_e32 v159, v159, v159
	v_exp_f32_e32 v159, v159
	s_nop 0
	v_add_f32_e32 v159, 1.0, v159
	v_rcp_f32_e32 v159, v159
	s_nop 0
	v_fma_f32 v159, v159, -2.0, 1.0
	v_bfi_b32 v153, s10, v154, v153
	v_mul_f32_e32 v136, 0.5, v136
	v_add_f32_e32 v153, 1.0, v153
	v_mul_f32_e32 v153, v136, v153
	v_bfi_b32 v136, s10, v158, v139
	v_mul_f32_e32 v137, 0.5, v137
	v_add_f32_e32 v136, 1.0, v136
	v_mul_f32_e32 v154, v137, v136
	v_bfi_b32 v136, s10, v157, v155
	v_mul_f32_e32 v132, 0.5, v132
	v_add_f32_e32 v136, 1.0, v136
	v_mul_f32_e32 v155, v132, v136
	v_bfi_b32 v136, s10, v150, v149
	v_mul_f32_e32 v130, 0.5, v130
	v_add_f32_e32 v136, 1.0, v136
	v_mul_f32_e32 v132, 0.5, v140
	v_mul_f32_e32 v140, v130, v136
	v_bfi_b32 v130, s10, v152, v131
	v_mul_f32_e32 v131, 0.5, v134
	v_bfi_b32 v134, s10, v148, v143
	v_add_f32_e32 v134, 1.0, v134
	v_add_f32_e32 v130, 1.0, v130
	v_mul_f32_e32 v143, v131, v134
	v_bfi_b32 v131, s10, v151, v135
	s_lshl_b64 s[2:3], s[2:3], 1
	v_mul_f32_e32 v132, v132, v130
	v_mul_f32_e32 v130, 0.5, v138
	v_add_f32_e32 v131, 1.0, v131
	s_add_u32 s2, s90, s2
	v_mul_f32_e32 v148, v130, v131
	s_addc_u32 s3, s91, s3
	v_lshlrev_b32_e32 v130, 1, v147
	v_mov_b32_e32 v131, v1
	v_lshl_add_u64 v[134:135], s[2:3], 0, v[130:131]
	v_bfi_b32 v130, s10, v159, v141
	v_mul_f32_e32 v133, 0.5, v133
	v_lshlrev_b32_e32 v137, 4, v142
	v_add_f32_e32 v130, 1.0, v130
	v_lshrrev_b32_e32 v136, 4, v146
	v_mul_f32_e32 v133, v133, v130
	v_or_b32_e32 v130, v137, v136
	v_ashrrev_i32_e32 v131, 31, v130
	v_lshlrev_b64 v[130:131], 10, v[130:131]
	v_lshl_add_u64 v[138:139], v[134:135], 0, v[130:131]
	v_cvt_pk_bf16_f32 v130, v143, v148
	v_cvt_pk_bf16_f32 v131, v153, v154
	v_cvt_pk_bf16_f32 v132, v140, v132
	v_cvt_pk_bf16_f32 v133, v155, v133
	global_store_dwordx4 v[138:139], v[130:133], off
	global_load_dwordx4 v[130:133], v[144:145], off offset:256
	s_waitcnt vmcnt(0)
	v_lshlrev_b32_e32 v138, 16, v130
	v_fma_f32 v126, v38, v138, v126
	v_mul_f32_e32 v138, 0x3d372713, v126
	v_mul_f32_e32 v138, v126, v138
	v_fma_f32 v138, v126, v138, v126
	v_mul_f32_e32 v138, 0x3f4c422a, v138
	v_mul_f32_e64 v139, |v138|, s76
	v_add_f32_e32 v139, v139, v139
	v_exp_f32_e32 v139, v139
	s_nop 0
	v_add_f32_e32 v139, 1.0, v139
	v_rcp_f32_e32 v139, v139
	s_nop 0
	v_fma_f32 v139, v139, -2.0, 1.0
	v_lshlrev_b32_e32 v140, 16, v132
	v_fma_f32 v122, v26, v140, v122
	v_mul_f32_e32 v140, 0x3d372713, v122
	v_mul_f32_e32 v140, v122, v140
	v_fma_f32 v140, v122, v140, v122
	v_mul_f32_e32 v140, 0x3f4c422a, v140
	v_mul_f32_e64 v141, |v140|, s76
	v_add_f32_e32 v141, v141, v141
	v_exp_f32_e32 v141, v141
	s_nop 0
	v_add_f32_e32 v141, 1.0, v141
	v_rcp_f32_e32 v141, v141
	s_nop 0
	v_fma_f32 v141, v141, -2.0, 1.0
	v_and_b32_e32 v130, 0xffff0000, v130
	v_fma_f32 v130, v39, v130, v127
	v_mul_f32_e32 v127, 0x3d372713, v130
	v_mul_f32_e32 v127, v130, v127
	v_fma_f32 v127, v130, v127, v130
	v_mul_f32_e32 v127, 0x3f4c422a, v127
	v_mul_f32_e64 v143, |v127|, s76
	v_add_f32_e32 v143, v143, v143
	v_exp_f32_e32 v143, v143
	s_nop 0
	v_add_f32_e32 v143, 1.0, v143
	v_rcp_f32_e32 v143, v143
	s_nop 0
	v_fma_f32 v143, v143, -2.0, 1.0
	v_and_b32_e32 v132, 0xffff0000, v132
	v_fma_f32 v132, v27, v132, v123
	v_mul_f32_e32 v123, 0x3d372713, v132
	v_mul_f32_e32 v123, v132, v123
	v_fma_f32 v123, v132, v123, v132
	v_mul_f32_e32 v123, 0x3f4c422a, v123
	v_mul_f32_e64 v144, |v123|, s76
	v_add_f32_e32 v144, v144, v144
	v_exp_f32_e32 v144, v144
	s_nop 0
	v_add_f32_e32 v144, 1.0, v144
	v_rcp_f32_e32 v144, v144
	s_nop 0
	v_fma_f32 v144, v144, -2.0, 1.0
	v_lshlrev_b32_e32 v145, 16, v131
	v_fma_f32 v128, v40, v145, v128
	v_mul_f32_e32 v145, 0x3d372713, v128
	v_mul_f32_e32 v145, v128, v145
	v_fma_f32 v145, v128, v145, v128
	v_mul_f32_e32 v145, 0x3f4c422a, v145
	v_mul_f32_e64 v147, |v145|, s76
	v_add_f32_e32 v147, v147, v147
	v_exp_f32_e32 v147, v147
	s_nop 0
	v_add_f32_e32 v147, 1.0, v147
	v_rcp_f32_e32 v147, v147
	s_nop 0
	v_fma_f32 v147, v147, -2.0, 1.0
	v_lshlrev_b32_e32 v148, 16, v133
	v_fma_f32 v124, v28, v148, v124
	v_mul_f32_e32 v148, 0x3d372713, v124
	v_mul_f32_e32 v148, v124, v148
	v_fma_f32 v148, v124, v148, v124
	v_mul_f32_e32 v148, 0x3f4c422a, v148
	v_mul_f32_e64 v149, |v148|, s76
	v_add_f32_e32 v149, v149, v149
	v_exp_f32_e32 v149, v149
	s_nop 0
	v_add_f32_e32 v149, 1.0, v149
	v_rcp_f32_e32 v149, v149
	s_nop 0
	v_fma_f32 v149, v149, -2.0, 1.0
	v_and_b32_e32 v131, 0xffff0000, v131
	v_fmac_f32_e32 v129, v41, v131
	v_mul_f32_e32 v131, 0x3d372713, v129
	v_mul_f32_e32 v131, v129, v131
	v_fma_f32 v131, v129, v131, v129
	v_mul_f32_e32 v131, 0x3f4c422a, v131
	v_mul_f32_e64 v150, |v131|, s76
	v_add_f32_e32 v150, v150, v150
	v_exp_f32_e32 v150, v150
	s_nop 0
	v_add_f32_e32 v150, 1.0, v150
	v_rcp_f32_e32 v150, v150
	s_nop 0
	v_fma_f32 v150, v150, -2.0, 1.0
	v_and_b32_e32 v133, 0xffff0000, v133
	v_fmac_f32_e32 v125, v29, v133
	v_mul_f32_e32 v133, 0x3d372713, v125
	v_mul_f32_e32 v133, v125, v133
	v_fma_f32 v133, v125, v133, v125
	v_mul_f32_e32 v133, 0x3f4c422a, v133
	v_mul_f32_e64 v151, |v133|, s76
	v_add_f32_e32 v151, v151, v151
	v_exp_f32_e32 v151, v151
	s_nop 0
	v_add_f32_e32 v151, 1.0, v151
	v_rcp_f32_e32 v151, v151
	s_nop 0
	v_fma_f32 v151, v151, -2.0, 1.0
	v_bfi_b32 v131, s10, v150, v131
	v_mul_f32_e32 v129, 0.5, v129
	v_add_f32_e32 v131, 1.0, v131
	v_mul_f32_e32 v129, v129, v131
	v_bfi_b32 v131, s10, v149, v148
	v_mul_f32_e32 v124, 0.5, v124
	v_add_f32_e32 v131, 1.0, v131
	v_mul_f32_e32 v131, v124, v131
	v_mul_f32_e32 v124, 0.5, v132
	v_bfi_b32 v132, s10, v141, v140
	v_mul_f32_e32 v122, 0.5, v122
	v_add_f32_e32 v132, 1.0, v132
	v_mul_f32_e32 v132, v122, v132
	v_bfi_b32 v122, s10, v144, v123
	v_mul_f32_e32 v123, 0.5, v126
	v_bfi_b32 v126, s10, v139, v138
	v_add_f32_e32 v126, 1.0, v126
	v_add_f32_e32 v122, 1.0, v122
	v_mul_f32_e32 v138, v123, v126
	v_bfi_b32 v123, s10, v143, v127
	v_mul_f32_e32 v124, v124, v122
	v_mul_f32_e32 v122, 0.5, v130
	v_add_f32_e32 v123, 1.0, v123
	v_mul_f32_e32 v139, v122, v123
	v_or_b32_e32 v122, 0x80, v146
	v_bfi_b32 v123, s10, v151, v133
	v_lshrrev_b32_e32 v130, 4, v122
	v_bfi_b32 v145, s10, v147, v145
	v_mul_f32_e32 v125, 0.5, v125
	v_add_f32_e32 v123, 1.0, v123
	v_or_b32_e32 v122, v137, v130
	v_mul_f32_e32 v128, 0.5, v128
	v_add_f32_e32 v145, 1.0, v145
	v_mul_f32_e32 v125, v125, v123
	v_ashrrev_i32_e32 v123, 31, v122
	v_mul_f32_e32 v128, v128, v145
	v_lshlrev_b64 v[122:123], 10, v[122:123]
	v_lshl_add_u64 v[126:127], v[134:135], 0, v[122:123]
	v_cvt_pk_bf16_f32 v123, v128, v129
	v_add_u32_e32 v128, 16, v142
	v_cvt_pk_bf16_f32 v122, v138, v139
	v_cvt_pk_bf16_f32 v124, v132, v124
	v_cvt_pk_bf16_f32 v125, v131, v125
	v_ashrrev_i32_e32 v129, 31, v128
	global_store_dwordx4 v[126:127], v[122:125], off
	s_nop 1
	v_lshlrev_b64 v[122:123], 9, v[128:129]
	v_lshl_add_u64 v[122:123], s[0:1], 0, v[122:123]
	v_lshl_add_u64 v[126:127], v[122:123], 0, v[0:1]
	global_load_dwordx4 v[122:125], v[126:127], off
	s_waitcnt vmcnt(0)
	v_lshlrev_b32_e32 v129, 16, v122
	v_fma_f32 v118, v38, v129, v118
	v_mul_f32_e32 v129, 0x3d372713, v118
	v_mul_f32_e32 v129, v118, v129
	v_fma_f32 v129, v118, v129, v118
	v_mul_f32_e32 v129, 0x3f4c422a, v129
	v_mul_f32_e64 v131, |v129|, s76
	v_add_f32_e32 v131, v131, v131
	v_exp_f32_e32 v131, v131
	s_nop 0
	v_add_f32_e32 v131, 1.0, v131
	v_rcp_f32_e32 v131, v131
	s_nop 0
	v_fma_f32 v131, v131, -2.0, 1.0
	v_lshlrev_b32_e32 v132, 16, v124
	v_fma_f32 v114, v26, v132, v114
	v_mul_f32_e32 v132, 0x3d372713, v114
	v_mul_f32_e32 v132, v114, v132
	v_fma_f32 v132, v114, v132, v114
	v_mul_f32_e32 v132, 0x3f4c422a, v132
	v_mul_f32_e64 v133, |v132|, s76
	v_add_f32_e32 v133, v133, v133
	v_exp_f32_e32 v133, v133
	s_nop 0
	v_add_f32_e32 v133, 1.0, v133
	v_rcp_f32_e32 v133, v133
	s_nop 0
	v_fma_f32 v133, v133, -2.0, 1.0
	v_and_b32_e32 v122, 0xffff0000, v122
	v_fma_f32 v122, v39, v122, v119
	v_mul_f32_e32 v119, 0x3d372713, v122
	v_mul_f32_e32 v119, v122, v119
	v_fma_f32 v119, v122, v119, v122
	v_mul_f32_e32 v119, 0x3f4c422a, v119
	v_mul_f32_e64 v137, |v119|, s76
	v_add_f32_e32 v137, v137, v137
	v_exp_f32_e32 v137, v137
	s_nop 0
	v_add_f32_e32 v137, 1.0, v137
	v_rcp_f32_e32 v137, v137
	s_nop 0
	v_fma_f32 v137, v137, -2.0, 1.0
	v_and_b32_e32 v124, 0xffff0000, v124
	v_fma_f32 v124, v27, v124, v115
	v_mul_f32_e32 v115, 0x3d372713, v124
	v_mul_f32_e32 v115, v124, v115
	v_fma_f32 v115, v124, v115, v124
	v_mul_f32_e32 v115, 0x3f4c422a, v115
	v_mul_f32_e64 v138, |v115|, s76
	v_add_f32_e32 v138, v138, v138
	v_exp_f32_e32 v138, v138
	s_nop 0
	v_add_f32_e32 v138, 1.0, v138
	v_rcp_f32_e32 v138, v138
	s_nop 0
	v_fma_f32 v138, v138, -2.0, 1.0
	v_lshlrev_b32_e32 v139, 16, v123
	v_fma_f32 v120, v40, v139, v120
	v_mul_f32_e32 v139, 0x3d372713, v120
	v_mul_f32_e32 v139, v120, v139
	v_fma_f32 v139, v120, v139, v120
	v_mul_f32_e32 v139, 0x3f4c422a, v139
	v_mul_f32_e64 v140, |v139|, s76
	v_add_f32_e32 v140, v140, v140
	v_exp_f32_e32 v140, v140
	s_nop 0
	v_add_f32_e32 v140, 1.0, v140
	v_rcp_f32_e32 v140, v140
	s_nop 0
	v_fma_f32 v140, v140, -2.0, 1.0
	v_lshlrev_b32_e32 v141, 16, v125
	v_fma_f32 v116, v28, v141, v116
	v_mul_f32_e32 v141, 0x3d372713, v116
	v_mul_f32_e32 v141, v116, v141
	v_fma_f32 v141, v116, v141, v116
	v_mul_f32_e32 v141, 0x3f4c422a, v141
	v_mul_f32_e64 v143, |v141|, s76
	v_add_f32_e32 v143, v143, v143
	v_exp_f32_e32 v143, v143
	s_nop 0
	v_add_f32_e32 v143, 1.0, v143
	v_rcp_f32_e32 v143, v143
	s_nop 0
	v_fma_f32 v143, v143, -2.0, 1.0
	v_and_b32_e32 v123, 0xffff0000, v123
	v_fmac_f32_e32 v121, v41, v123
	v_mul_f32_e32 v123, 0x3d372713, v121
	v_mul_f32_e32 v123, v121, v123
	v_fma_f32 v123, v121, v123, v121
	v_mul_f32_e32 v123, 0x3f4c422a, v123
	v_mul_f32_e64 v144, |v123|, s76
	v_add_f32_e32 v144, v144, v144
	v_exp_f32_e32 v144, v144
	s_nop 0
	v_add_f32_e32 v144, 1.0, v144
	v_rcp_f32_e32 v144, v144
	s_nop 0
	v_fma_f32 v144, v144, -2.0, 1.0
	v_and_b32_e32 v125, 0xffff0000, v125
	v_fmac_f32_e32 v117, v29, v125
	v_mul_f32_e32 v125, 0x3d372713, v117
	v_mul_f32_e32 v125, v117, v125
	v_fma_f32 v125, v117, v125, v117
	v_mul_f32_e32 v125, 0x3f4c422a, v125
	v_mul_f32_e64 v145, |v125|, s76
	v_add_f32_e32 v145, v145, v145
	v_exp_f32_e32 v145, v145
	s_nop 0
	v_add_f32_e32 v145, 1.0, v145
	v_rcp_f32_e32 v145, v145
	s_nop 0
	v_fma_f32 v145, v145, -2.0, 1.0
	v_bfi_b32 v139, s10, v140, v139
	v_mul_f32_e32 v120, 0.5, v120
	v_add_f32_e32 v139, 1.0, v139
	v_mul_f32_e32 v139, v120, v139
	v_bfi_b32 v120, s10, v144, v123
	v_mul_f32_e32 v121, 0.5, v121
	v_add_f32_e32 v120, 1.0, v120
	v_mul_f32_e32 v123, v121, v120
	v_bfi_b32 v120, s10, v143, v141
	v_mul_f32_e32 v116, 0.5, v116
	v_add_f32_e32 v120, 1.0, v120
	v_mul_f32_e32 v140, v116, v120
	v_bfi_b32 v120, s10, v133, v132
	v_mul_f32_e32 v114, 0.5, v114
	v_add_f32_e32 v120, 1.0, v120
	v_mul_f32_e32 v116, 0.5, v124
	v_mul_f32_e32 v124, v114, v120
	v_bfi_b32 v114, s10, v138, v115
	v_mul_f32_e32 v115, 0.5, v118
	v_bfi_b32 v118, s10, v131, v129
	v_add_f32_e32 v114, 1.0, v114
	v_add_f32_e32 v118, 1.0, v118
	v_mul_f32_e32 v116, v116, v114
	v_mul_f32_e32 v114, 0.5, v122
	v_mul_f32_e32 v122, v115, v118
	v_bfi_b32 v115, s10, v137, v119
	v_add_f32_e32 v115, 1.0, v115
	v_mul_f32_e32 v119, v114, v115
	v_bfi_b32 v114, s10, v145, v125
	v_mul_f32_e32 v117, 0.5, v117
	v_lshlrev_b32_e32 v118, 4, v128
	v_add_f32_e32 v114, 1.0, v114
	v_mul_f32_e32 v117, v117, v114
	v_or_b32_e32 v114, v118, v136
	v_ashrrev_i32_e32 v115, 31, v114
	v_lshlrev_b64 v[114:115], 10, v[114:115]
	v_lshl_add_u64 v[120:121], v[134:135], 0, v[114:115]
	v_cvt_pk_bf16_f32 v114, v122, v119
	v_cvt_pk_bf16_f32 v115, v139, v123
	v_cvt_pk_bf16_f32 v116, v124, v116
	v_cvt_pk_bf16_f32 v117, v140, v117
	global_store_dwordx4 v[120:121], v[114:117], off
	global_load_dwordx4 v[114:117], v[126:127], off offset:256
	s_waitcnt vmcnt(0)
	v_lshlrev_b32_e32 v119, 16, v114
	v_fma_f32 v110, v38, v119, v110
	v_mul_f32_e32 v119, 0x3d372713, v110
	v_mul_f32_e32 v119, v110, v119
	v_fma_f32 v119, v110, v119, v110
	v_mul_f32_e32 v119, 0x3f4c422a, v119
	v_mul_f32_e64 v120, |v119|, s76
	v_add_f32_e32 v120, v120, v120
	v_exp_f32_e32 v120, v120
	s_nop 0
	v_add_f32_e32 v120, 1.0, v120
	v_rcp_f32_e32 v120, v120
	s_nop 0
	v_fma_f32 v120, v120, -2.0, 1.0
	v_lshlrev_b32_e32 v121, 16, v116
	v_fma_f32 v106, v26, v121, v106
	v_mul_f32_e32 v121, 0x3d372713, v106
	v_mul_f32_e32 v121, v106, v121
	v_fma_f32 v121, v106, v121, v106
	v_mul_f32_e32 v121, 0x3f4c422a, v121
	v_mul_f32_e64 v122, |v121|, s76
	v_add_f32_e32 v122, v122, v122
	v_exp_f32_e32 v122, v122
	s_nop 0
	v_add_f32_e32 v122, 1.0, v122
	v_rcp_f32_e32 v122, v122
	s_nop 0
	v_fma_f32 v122, v122, -2.0, 1.0
	v_and_b32_e32 v114, 0xffff0000, v114
	v_fma_f32 v114, v39, v114, v111
	v_mul_f32_e32 v111, 0x3d372713, v114
	v_mul_f32_e32 v111, v114, v111
	v_fma_f32 v111, v114, v111, v114
	v_mul_f32_e32 v111, 0x3f4c422a, v111
	v_mul_f32_e64 v123, |v111|, s76
	v_add_f32_e32 v123, v123, v123
	v_exp_f32_e32 v123, v123
	s_nop 0
	v_add_f32_e32 v123, 1.0, v123
	v_rcp_f32_e32 v123, v123
	s_nop 0
	v_fma_f32 v123, v123, -2.0, 1.0
	v_and_b32_e32 v116, 0xffff0000, v116
	v_fma_f32 v116, v27, v116, v107
	v_mul_f32_e32 v107, 0x3d372713, v116
	v_mul_f32_e32 v107, v116, v107
	v_fma_f32 v107, v116, v107, v116
	v_mul_f32_e32 v107, 0x3f4c422a, v107
	v_mul_f32_e64 v124, |v107|, s76
	v_add_f32_e32 v124, v124, v124
	v_exp_f32_e32 v124, v124
	s_nop 0
	v_add_f32_e32 v124, 1.0, v124
	v_rcp_f32_e32 v124, v124
	s_nop 0
	v_fma_f32 v124, v124, -2.0, 1.0
	v_lshlrev_b32_e32 v125, 16, v115
	v_fma_f32 v112, v40, v125, v112
	v_mul_f32_e32 v125, 0x3d372713, v112
	v_mul_f32_e32 v125, v112, v125
	v_fma_f32 v125, v112, v125, v112
	v_mul_f32_e32 v125, 0x3f4c422a, v125
	v_mul_f32_e64 v126, |v125|, s76
	v_add_f32_e32 v126, v126, v126
	v_exp_f32_e32 v126, v126
	s_nop 0
	v_add_f32_e32 v126, 1.0, v126
	v_rcp_f32_e32 v126, v126
	s_nop 0
	v_fma_f32 v126, v126, -2.0, 1.0
	v_lshlrev_b32_e32 v127, 16, v117
	v_fma_f32 v108, v28, v127, v108
	v_mul_f32_e32 v127, 0x3d372713, v108
	v_mul_f32_e32 v127, v108, v127
	v_fma_f32 v127, v108, v127, v108
	v_mul_f32_e32 v127, 0x3f4c422a, v127
	v_mul_f32_e64 v128, |v127|, s76
	v_add_f32_e32 v128, v128, v128
	v_exp_f32_e32 v128, v128
	s_nop 0
	v_add_f32_e32 v128, 1.0, v128
	v_rcp_f32_e32 v128, v128
	s_nop 0
	v_fma_f32 v128, v128, -2.0, 1.0
	v_and_b32_e32 v115, 0xffff0000, v115
	v_fmac_f32_e32 v113, v41, v115
	v_mul_f32_e32 v115, 0x3d372713, v113
	v_mul_f32_e32 v115, v113, v115
	v_fma_f32 v115, v113, v115, v113
	v_mul_f32_e32 v115, 0x3f4c422a, v115
	v_mul_f32_e64 v129, |v115|, s76
	v_add_f32_e32 v129, v129, v129
	v_exp_f32_e32 v129, v129
	s_nop 0
	v_add_f32_e32 v129, 1.0, v129
	v_rcp_f32_e32 v129, v129
	s_nop 0
	v_fma_f32 v129, v129, -2.0, 1.0
	v_and_b32_e32 v117, 0xffff0000, v117
	v_fmac_f32_e32 v109, v29, v117
	v_mul_f32_e32 v117, 0x3d372713, v109
	v_mul_f32_e32 v117, v109, v117
	v_fma_f32 v117, v109, v117, v109
	v_mul_f32_e32 v117, 0x3f4c422a, v117
	v_mul_f32_e64 v131, |v117|, s76
	v_add_f32_e32 v131, v131, v131
	v_exp_f32_e32 v131, v131
	s_nop 0
	v_add_f32_e32 v131, 1.0, v131
	v_rcp_f32_e32 v131, v131
	s_nop 0
	v_fma_f32 v131, v131, -2.0, 1.0
	v_bfi_b32 v115, s10, v129, v115
	v_mul_f32_e32 v113, 0.5, v113
	v_add_f32_e32 v115, 1.0, v115
	v_mul_f32_e32 v113, v113, v115
	v_bfi_b32 v115, s10, v128, v127
	v_mul_f32_e32 v108, 0.5, v108
	v_add_f32_e32 v115, 1.0, v115
	v_mul_f32_e32 v115, v108, v115
	v_mul_f32_e32 v108, 0.5, v116
	v_bfi_b32 v116, s10, v122, v121
	v_mul_f32_e32 v106, 0.5, v106
	v_add_f32_e32 v116, 1.0, v116
	v_mul_f32_e32 v116, v106, v116
	v_bfi_b32 v106, s10, v124, v107
	v_mul_f32_e32 v107, 0.5, v110
	v_bfi_b32 v110, s10, v120, v119
	v_add_f32_e32 v106, 1.0, v106
	v_add_f32_e32 v110, 1.0, v110
	v_mul_f32_e32 v108, v108, v106
	v_mul_f32_e32 v106, 0.5, v114
	v_mul_f32_e32 v114, v107, v110
	v_bfi_b32 v107, s10, v123, v111
	v_add_f32_e32 v107, 1.0, v107
	v_mul_f32_e32 v119, v106, v107
	v_bfi_b32 v106, s10, v131, v117
	v_mul_f32_e32 v109, 0.5, v109
	v_add_f32_e32 v106, 1.0, v106
	v_bfi_b32 v125, s10, v126, v125
	v_mul_f32_e32 v109, v109, v106
	v_or_b32_e32 v106, v118, v130
	v_mul_f32_e32 v112, 0.5, v112
	v_add_f32_e32 v125, 1.0, v125
	v_ashrrev_i32_e32 v107, 31, v106
	v_mul_f32_e32 v112, v112, v125
	v_lshlrev_b64 v[106:107], 10, v[106:107]
	v_lshl_add_u64 v[110:111], v[134:135], 0, v[106:107]
	v_cvt_pk_bf16_f32 v107, v112, v113
	v_add_u32_e32 v112, 32, v142
	v_cvt_pk_bf16_f32 v106, v114, v119
	v_cvt_pk_bf16_f32 v108, v116, v108
	v_cvt_pk_bf16_f32 v109, v115, v109
	v_ashrrev_i32_e32 v113, 31, v112
	global_store_dwordx4 v[110:111], v[106:109], off
	s_nop 1
	v_lshlrev_b64 v[106:107], 9, v[112:113]
	v_lshl_add_u64 v[106:107], s[0:1], 0, v[106:107]
	v_lshl_add_u64 v[110:111], v[106:107], 0, v[0:1]
	global_load_dwordx4 v[106:109], v[110:111], off
	s_waitcnt vmcnt(0)
	v_lshlrev_b32_e32 v113, 16, v106
	v_fma_f32 v102, v38, v113, v102
	v_mul_f32_e32 v113, 0x3d372713, v102
	v_mul_f32_e32 v113, v102, v113
	v_fma_f32 v113, v102, v113, v102
	v_mul_f32_e32 v113, 0x3f4c422a, v113
	v_mul_f32_e64 v114, |v113|, s76
	v_add_f32_e32 v114, v114, v114
	v_exp_f32_e32 v114, v114
	s_nop 0
	v_add_f32_e32 v114, 1.0, v114
	v_rcp_f32_e32 v114, v114
	s_nop 0
	v_fma_f32 v114, v114, -2.0, 1.0
	v_lshlrev_b32_e32 v115, 16, v108
	v_fma_f32 v98, v26, v115, v98
	v_mul_f32_e32 v115, 0x3d372713, v98
	v_mul_f32_e32 v115, v98, v115
	v_fma_f32 v115, v98, v115, v98
	v_mul_f32_e32 v115, 0x3f4c422a, v115
	v_mul_f32_e64 v116, |v115|, s76
	v_add_f32_e32 v116, v116, v116
	v_exp_f32_e32 v116, v116
	s_nop 0
	v_add_f32_e32 v116, 1.0, v116
	v_rcp_f32_e32 v116, v116
	s_nop 0
	v_fma_f32 v116, v116, -2.0, 1.0
	v_and_b32_e32 v106, 0xffff0000, v106
	v_fma_f32 v106, v39, v106, v103
	v_mul_f32_e32 v103, 0x3d372713, v106
	v_mul_f32_e32 v103, v106, v103
	v_fma_f32 v103, v106, v103, v106
	v_mul_f32_e32 v103, 0x3f4c422a, v103
	v_mul_f32_e64 v117, |v103|, s76
	v_add_f32_e32 v117, v117, v117
	v_exp_f32_e32 v117, v117
	s_nop 0
	v_add_f32_e32 v117, 1.0, v117
	v_rcp_f32_e32 v117, v117
	s_nop 0
	v_fma_f32 v117, v117, -2.0, 1.0
	v_and_b32_e32 v108, 0xffff0000, v108
	v_fma_f32 v108, v27, v108, v99
	v_mul_f32_e32 v99, 0x3d372713, v108
	v_mul_f32_e32 v99, v108, v99
	v_fma_f32 v99, v108, v99, v108
	v_mul_f32_e32 v99, 0x3f4c422a, v99
	v_mul_f32_e64 v118, |v99|, s76
	v_add_f32_e32 v118, v118, v118
	v_exp_f32_e32 v118, v118
	s_nop 0
	v_add_f32_e32 v118, 1.0, v118
	v_rcp_f32_e32 v118, v118
	s_nop 0
	v_fma_f32 v118, v118, -2.0, 1.0
	v_lshlrev_b32_e32 v119, 16, v107
	v_fma_f32 v104, v40, v119, v104
	v_mul_f32_e32 v119, 0x3d372713, v104
	v_mul_f32_e32 v119, v104, v119
	v_fma_f32 v119, v104, v119, v104
	v_mul_f32_e32 v119, 0x3f4c422a, v119
	v_mul_f32_e64 v120, |v119|, s76
	v_add_f32_e32 v120, v120, v120
	v_exp_f32_e32 v120, v120
	s_nop 0
	v_add_f32_e32 v120, 1.0, v120
	v_rcp_f32_e32 v120, v120
	s_nop 0
	v_fma_f32 v120, v120, -2.0, 1.0
	v_lshlrev_b32_e32 v121, 16, v109
	v_fma_f32 v100, v28, v121, v100
	v_mul_f32_e32 v121, 0x3d372713, v100
	v_mul_f32_e32 v121, v100, v121
	v_fma_f32 v121, v100, v121, v100
	v_mul_f32_e32 v121, 0x3f4c422a, v121
	v_mul_f32_e64 v122, |v121|, s76
	v_add_f32_e32 v122, v122, v122
	v_exp_f32_e32 v122, v122
	s_nop 0
	v_add_f32_e32 v122, 1.0, v122
	v_rcp_f32_e32 v122, v122
	s_nop 0
	v_fma_f32 v122, v122, -2.0, 1.0
	v_and_b32_e32 v107, 0xffff0000, v107
	v_fmac_f32_e32 v105, v41, v107
	v_mul_f32_e32 v107, 0x3d372713, v105
	v_mul_f32_e32 v107, v105, v107
	v_fma_f32 v107, v105, v107, v105
	v_mul_f32_e32 v107, 0x3f4c422a, v107
	v_mul_f32_e64 v123, |v107|, s76
	v_add_f32_e32 v123, v123, v123
	v_exp_f32_e32 v123, v123
	s_nop 0
	v_add_f32_e32 v123, 1.0, v123
	v_rcp_f32_e32 v123, v123
	s_nop 0
	v_fma_f32 v123, v123, -2.0, 1.0
	v_and_b32_e32 v109, 0xffff0000, v109
	v_fmac_f32_e32 v101, v29, v109
	v_mul_f32_e32 v109, 0x3d372713, v101
	v_mul_f32_e32 v109, v101, v109
	v_fma_f32 v109, v101, v109, v101
	v_mul_f32_e32 v109, 0x3f4c422a, v109
	v_mul_f32_e64 v124, |v109|, s76
	v_add_f32_e32 v124, v124, v124
	v_exp_f32_e32 v124, v124
	s_nop 0
	v_add_f32_e32 v124, 1.0, v124
	v_rcp_f32_e32 v124, v124
	s_nop 0
	v_fma_f32 v124, v124, -2.0, 1.0
	v_bfi_b32 v119, s10, v120, v119
	v_mul_f32_e32 v104, 0.5, v104
	v_add_f32_e32 v119, 1.0, v119
	v_mul_f32_e32 v119, v104, v119
	v_bfi_b32 v104, s10, v123, v107
	v_mul_f32_e32 v105, 0.5, v105
	v_add_f32_e32 v104, 1.0, v104
	v_mul_f32_e32 v107, v105, v104
	v_bfi_b32 v104, s10, v122, v121
	v_mul_f32_e32 v100, 0.5, v100
	v_add_f32_e32 v104, 1.0, v104
	v_mul_f32_e32 v120, v100, v104
	v_bfi_b32 v104, s10, v116, v115
	v_mul_f32_e32 v98, 0.5, v98
	v_add_f32_e32 v104, 1.0, v104
	v_mul_f32_e32 v100, 0.5, v108
	v_mul_f32_e32 v108, v98, v104
	v_bfi_b32 v98, s10, v118, v99
	v_mul_f32_e32 v99, 0.5, v102
	v_bfi_b32 v102, s10, v114, v113
	v_add_f32_e32 v98, 1.0, v98
	v_add_f32_e32 v102, 1.0, v102
	v_mul_f32_e32 v100, v100, v98
	v_mul_f32_e32 v98, 0.5, v106
	v_mul_f32_e32 v106, v99, v102
	v_bfi_b32 v99, s10, v117, v103
	v_add_f32_e32 v99, 1.0, v99
	v_mul_f32_e32 v103, v98, v99
	v_bfi_b32 v98, s10, v124, v109
	v_mul_f32_e32 v101, 0.5, v101
	v_lshlrev_b32_e32 v102, 4, v112
	v_add_f32_e32 v98, 1.0, v98
	v_mul_f32_e32 v101, v101, v98
	v_or_b32_e32 v98, v102, v136
	v_ashrrev_i32_e32 v99, 31, v98
	v_lshlrev_b64 v[98:99], 10, v[98:99]
	v_lshl_add_u64 v[104:105], v[134:135], 0, v[98:99]
	v_cvt_pk_bf16_f32 v98, v106, v103
	v_cvt_pk_bf16_f32 v99, v119, v107
	v_cvt_pk_bf16_f32 v100, v108, v100
	v_cvt_pk_bf16_f32 v101, v120, v101
	global_store_dwordx4 v[104:105], v[98:101], off
	global_load_dwordx4 v[98:101], v[110:111], off offset:256
	s_waitcnt vmcnt(0)
	v_lshlrev_b32_e32 v103, 16, v98
	v_fma_f32 v94, v38, v103, v94
	v_mul_f32_e32 v103, 0x3d372713, v94
	v_mul_f32_e32 v103, v94, v103
	v_fma_f32 v103, v94, v103, v94
	v_mul_f32_e32 v103, 0x3f4c422a, v103
	v_mul_f32_e64 v104, |v103|, s76
	v_add_f32_e32 v104, v104, v104
	v_exp_f32_e32 v104, v104
	s_nop 0
	v_add_f32_e32 v104, 1.0, v104
	v_rcp_f32_e32 v104, v104
	s_nop 0
	v_fma_f32 v104, v104, -2.0, 1.0
	v_lshlrev_b32_e32 v105, 16, v100
	v_fma_f32 v90, v26, v105, v90
	v_mul_f32_e32 v105, 0x3d372713, v90
	v_mul_f32_e32 v105, v90, v105
	v_fma_f32 v105, v90, v105, v90
	v_mul_f32_e32 v105, 0x3f4c422a, v105
	v_mul_f32_e64 v106, |v105|, s76
	v_add_f32_e32 v106, v106, v106
	v_exp_f32_e32 v106, v106
	s_nop 0
	v_add_f32_e32 v106, 1.0, v106
	v_rcp_f32_e32 v106, v106
	s_nop 0
	v_fma_f32 v106, v106, -2.0, 1.0
	v_and_b32_e32 v98, 0xffff0000, v98
	v_fma_f32 v98, v39, v98, v95
	v_mul_f32_e32 v95, 0x3d372713, v98
	v_mul_f32_e32 v95, v98, v95
	v_fma_f32 v95, v98, v95, v98
	v_mul_f32_e32 v95, 0x3f4c422a, v95
	v_mul_f32_e64 v107, |v95|, s76
	v_add_f32_e32 v107, v107, v107
	v_exp_f32_e32 v107, v107
	s_nop 0
	v_add_f32_e32 v107, 1.0, v107
	v_rcp_f32_e32 v107, v107
	s_nop 0
	v_fma_f32 v107, v107, -2.0, 1.0
	v_and_b32_e32 v100, 0xffff0000, v100
	v_fma_f32 v100, v27, v100, v91
	v_mul_f32_e32 v91, 0x3d372713, v100
	v_mul_f32_e32 v91, v100, v91
	v_fma_f32 v91, v100, v91, v100
	v_mul_f32_e32 v91, 0x3f4c422a, v91
	v_mul_f32_e64 v108, |v91|, s76
	v_add_f32_e32 v108, v108, v108
	v_exp_f32_e32 v108, v108
	s_nop 0
	v_add_f32_e32 v108, 1.0, v108
	v_rcp_f32_e32 v108, v108
	s_nop 0
	v_fma_f32 v108, v108, -2.0, 1.0
	v_lshlrev_b32_e32 v109, 16, v99
	v_fma_f32 v96, v40, v109, v96
	v_mul_f32_e32 v109, 0x3d372713, v96
	v_mul_f32_e32 v109, v96, v109
	v_fma_f32 v109, v96, v109, v96
	v_mul_f32_e32 v109, 0x3f4c422a, v109
	v_mul_f32_e64 v110, |v109|, s76
	v_add_f32_e32 v110, v110, v110
	v_exp_f32_e32 v110, v110
	s_nop 0
	v_add_f32_e32 v110, 1.0, v110
	v_rcp_f32_e32 v110, v110
	s_nop 0
	v_fma_f32 v110, v110, -2.0, 1.0
	v_lshlrev_b32_e32 v111, 16, v101
	v_fma_f32 v92, v28, v111, v92
	v_mul_f32_e32 v111, 0x3d372713, v92
	v_mul_f32_e32 v111, v92, v111
	v_fma_f32 v111, v92, v111, v92
	v_mul_f32_e32 v111, 0x3f4c422a, v111
	v_mul_f32_e64 v112, |v111|, s76
	v_add_f32_e32 v112, v112, v112
	v_exp_f32_e32 v112, v112
	s_nop 0
	v_add_f32_e32 v112, 1.0, v112
	v_rcp_f32_e32 v112, v112
	s_nop 0
	v_fma_f32 v112, v112, -2.0, 1.0
	v_and_b32_e32 v99, 0xffff0000, v99
	v_fmac_f32_e32 v97, v41, v99
	v_mul_f32_e32 v99, 0x3d372713, v97
	v_mul_f32_e32 v99, v97, v99
	v_fma_f32 v99, v97, v99, v97
	v_mul_f32_e32 v99, 0x3f4c422a, v99
	v_mul_f32_e64 v113, |v99|, s76
	v_add_f32_e32 v113, v113, v113
	v_exp_f32_e32 v113, v113
	s_nop 0
	v_add_f32_e32 v113, 1.0, v113
	v_rcp_f32_e32 v113, v113
	s_nop 0
	v_fma_f32 v113, v113, -2.0, 1.0
	v_and_b32_e32 v101, 0xffff0000, v101
	v_fmac_f32_e32 v93, v29, v101
	v_mul_f32_e32 v101, 0x3d372713, v93
	v_mul_f32_e32 v101, v93, v101
	v_fma_f32 v101, v93, v101, v93
	v_mul_f32_e32 v101, 0x3f4c422a, v101
	v_mul_f32_e64 v114, |v101|, s76
	v_add_f32_e32 v114, v114, v114
	v_exp_f32_e32 v114, v114
	s_nop 0
	v_add_f32_e32 v114, 1.0, v114
	v_rcp_f32_e32 v114, v114
	s_nop 0
	v_fma_f32 v114, v114, -2.0, 1.0
	v_bfi_b32 v99, s10, v113, v99
	v_mul_f32_e32 v97, 0.5, v97
	v_add_f32_e32 v99, 1.0, v99
	v_mul_f32_e32 v97, v97, v99
	v_bfi_b32 v99, s10, v112, v111
	v_mul_f32_e32 v92, 0.5, v92
	v_add_f32_e32 v99, 1.0, v99
	v_mul_f32_e32 v99, v92, v99
	v_mul_f32_e32 v92, 0.5, v100
	v_bfi_b32 v100, s10, v106, v105
	v_mul_f32_e32 v90, 0.5, v90
	v_add_f32_e32 v100, 1.0, v100
	v_mul_f32_e32 v100, v90, v100
	v_bfi_b32 v90, s10, v108, v91
	v_mul_f32_e32 v91, 0.5, v94
	v_bfi_b32 v94, s10, v104, v103
	v_add_f32_e32 v90, 1.0, v90
	v_add_f32_e32 v94, 1.0, v94
	v_mul_f32_e32 v92, v92, v90
	v_mul_f32_e32 v90, 0.5, v98
	v_mul_f32_e32 v98, v91, v94
	v_bfi_b32 v91, s10, v107, v95
	v_add_f32_e32 v91, 1.0, v91
	v_mul_f32_e32 v103, v90, v91
	v_bfi_b32 v90, s10, v114, v101
	v_mul_f32_e32 v93, 0.5, v93
	v_add_f32_e32 v90, 1.0, v90
	v_bfi_b32 v109, s10, v110, v109
	v_mul_f32_e32 v93, v93, v90
	v_or_b32_e32 v90, v102, v130
	v_mul_f32_e32 v96, 0.5, v96
	v_add_f32_e32 v109, 1.0, v109
	v_ashrrev_i32_e32 v91, 31, v90
	v_mul_f32_e32 v96, v96, v109
	v_lshlrev_b64 v[90:91], 10, v[90:91]
	v_lshl_add_u64 v[94:95], v[134:135], 0, v[90:91]
	v_cvt_pk_bf16_f32 v91, v96, v97
	v_add_u32_e32 v96, 48, v142
	v_cvt_pk_bf16_f32 v90, v98, v103
	v_cvt_pk_bf16_f32 v92, v100, v92
	v_cvt_pk_bf16_f32 v93, v99, v93
	v_ashrrev_i32_e32 v97, 31, v96
	global_store_dwordx4 v[94:95], v[90:93], off
	s_nop 1
	v_lshlrev_b64 v[90:91], 9, v[96:97]
	v_lshl_add_u64 v[90:91], s[0:1], 0, v[90:91]
	v_lshl_add_u64 v[94:95], v[90:91], 0, v[0:1]
	global_load_dwordx4 v[90:93], v[94:95], off
	s_waitcnt vmcnt(0)
	v_lshlrev_b32_e32 v97, 16, v90
	v_fma_f32 v86, v38, v97, v86
	v_mul_f32_e32 v97, 0x3d372713, v86
	v_mul_f32_e32 v97, v86, v97
	v_fma_f32 v97, v86, v97, v86
	v_mul_f32_e32 v97, 0x3f4c422a, v97
	v_mul_f32_e64 v98, |v97|, s76
	v_add_f32_e32 v98, v98, v98
	v_exp_f32_e32 v98, v98
	s_nop 0
	v_add_f32_e32 v98, 1.0, v98
	v_rcp_f32_e32 v98, v98
	s_nop 0
	v_fma_f32 v98, v98, -2.0, 1.0
	v_lshlrev_b32_e32 v99, 16, v92
	v_fma_f32 v82, v26, v99, v82
	v_mul_f32_e32 v99, 0x3d372713, v82
	v_mul_f32_e32 v99, v82, v99
	v_fma_f32 v99, v82, v99, v82
	v_mul_f32_e32 v99, 0x3f4c422a, v99
	v_mul_f32_e64 v100, |v99|, s76
	v_add_f32_e32 v100, v100, v100
	v_exp_f32_e32 v100, v100
	s_nop 0
	v_add_f32_e32 v100, 1.0, v100
	v_rcp_f32_e32 v100, v100
	s_nop 0
	v_fma_f32 v100, v100, -2.0, 1.0
	v_and_b32_e32 v90, 0xffff0000, v90
	v_fma_f32 v90, v39, v90, v87
	v_mul_f32_e32 v87, 0x3d372713, v90
	v_mul_f32_e32 v87, v90, v87
	v_fma_f32 v87, v90, v87, v90
	v_mul_f32_e32 v87, 0x3f4c422a, v87
	v_mul_f32_e64 v101, |v87|, s76
	v_add_f32_e32 v101, v101, v101
	v_exp_f32_e32 v101, v101
	s_nop 0
	v_add_f32_e32 v101, 1.0, v101
	v_rcp_f32_e32 v101, v101
	s_nop 0
	v_fma_f32 v101, v101, -2.0, 1.0
	v_and_b32_e32 v92, 0xffff0000, v92
	v_fma_f32 v92, v27, v92, v83
	v_mul_f32_e32 v83, 0x3d372713, v92
	v_mul_f32_e32 v83, v92, v83
	v_fma_f32 v83, v92, v83, v92
	v_mul_f32_e32 v83, 0x3f4c422a, v83
	v_mul_f32_e64 v102, |v83|, s76
	v_add_f32_e32 v102, v102, v102
	v_exp_f32_e32 v102, v102
	s_nop 0
	v_add_f32_e32 v102, 1.0, v102
	v_rcp_f32_e32 v102, v102
	s_nop 0
	v_fma_f32 v102, v102, -2.0, 1.0
	v_lshlrev_b32_e32 v103, 16, v91
	v_fma_f32 v88, v40, v103, v88
	v_mul_f32_e32 v103, 0x3d372713, v88
	v_mul_f32_e32 v103, v88, v103
	v_fma_f32 v103, v88, v103, v88
	v_mul_f32_e32 v103, 0x3f4c422a, v103
	v_mul_f32_e64 v104, |v103|, s76
	v_add_f32_e32 v104, v104, v104
	v_exp_f32_e32 v104, v104
	s_nop 0
	v_add_f32_e32 v104, 1.0, v104
	v_rcp_f32_e32 v104, v104
	s_nop 0
	v_fma_f32 v104, v104, -2.0, 1.0
	v_lshlrev_b32_e32 v105, 16, v93
	v_fma_f32 v84, v28, v105, v84
	v_mul_f32_e32 v105, 0x3d372713, v84
	v_mul_f32_e32 v105, v84, v105
	v_fma_f32 v105, v84, v105, v84
	v_mul_f32_e32 v105, 0x3f4c422a, v105
	v_mul_f32_e64 v106, |v105|, s76
	v_add_f32_e32 v106, v106, v106
	v_exp_f32_e32 v106, v106
	s_nop 0
	v_add_f32_e32 v106, 1.0, v106
	v_rcp_f32_e32 v106, v106
	s_nop 0
	v_fma_f32 v106, v106, -2.0, 1.0
	v_and_b32_e32 v91, 0xffff0000, v91
	v_fmac_f32_e32 v89, v41, v91
	v_mul_f32_e32 v91, 0x3d372713, v89
	v_mul_f32_e32 v91, v89, v91
	v_fma_f32 v91, v89, v91, v89
	v_mul_f32_e32 v91, 0x3f4c422a, v91
	v_mul_f32_e64 v107, |v91|, s76
	v_add_f32_e32 v107, v107, v107
	v_exp_f32_e32 v107, v107
	s_nop 0
	v_add_f32_e32 v107, 1.0, v107
	v_rcp_f32_e32 v107, v107
	s_nop 0
	v_fma_f32 v107, v107, -2.0, 1.0
	v_and_b32_e32 v93, 0xffff0000, v93
	v_fmac_f32_e32 v85, v29, v93
	v_mul_f32_e32 v93, 0x3d372713, v85
	v_mul_f32_e32 v93, v85, v93
	v_fma_f32 v93, v85, v93, v85
	v_mul_f32_e32 v93, 0x3f4c422a, v93
	v_mul_f32_e64 v108, |v93|, s76
	v_add_f32_e32 v108, v108, v108
	v_exp_f32_e32 v108, v108
	s_nop 0
	v_add_f32_e32 v108, 1.0, v108
	v_rcp_f32_e32 v108, v108
	s_nop 0
	v_fma_f32 v108, v108, -2.0, 1.0
	v_bfi_b32 v103, s10, v104, v103
	v_mul_f32_e32 v88, 0.5, v88
	v_add_f32_e32 v103, 1.0, v103
	v_mul_f32_e32 v103, v88, v103
	v_bfi_b32 v88, s10, v107, v91
	v_mul_f32_e32 v89, 0.5, v89
	v_add_f32_e32 v88, 1.0, v88
	v_mul_f32_e32 v91, v89, v88
	v_bfi_b32 v88, s10, v106, v105
	v_mul_f32_e32 v84, 0.5, v84
	v_add_f32_e32 v88, 1.0, v88
	v_mul_f32_e32 v104, v84, v88
	v_bfi_b32 v88, s10, v100, v99
	v_mul_f32_e32 v82, 0.5, v82
	v_add_f32_e32 v88, 1.0, v88
	v_mul_f32_e32 v84, 0.5, v92
	v_mul_f32_e32 v92, v82, v88
	v_bfi_b32 v82, s10, v102, v83
	v_mul_f32_e32 v83, 0.5, v86
	v_bfi_b32 v86, s10, v98, v97
	v_add_f32_e32 v82, 1.0, v82
	v_add_f32_e32 v86, 1.0, v86
	v_mul_f32_e32 v84, v84, v82
	v_mul_f32_e32 v82, 0.5, v90
	v_mul_f32_e32 v90, v83, v86
	v_bfi_b32 v83, s10, v101, v87
	v_add_f32_e32 v83, 1.0, v83
	v_mul_f32_e32 v87, v82, v83
	v_bfi_b32 v82, s10, v108, v93
	v_mul_f32_e32 v85, 0.5, v85
	v_lshlrev_b32_e32 v86, 4, v96
	v_add_f32_e32 v82, 1.0, v82
	v_mul_f32_e32 v85, v85, v82
	v_or_b32_e32 v82, v86, v136
	v_ashrrev_i32_e32 v83, 31, v82
	v_lshlrev_b64 v[82:83], 10, v[82:83]
	v_lshl_add_u64 v[88:89], v[134:135], 0, v[82:83]
	v_cvt_pk_bf16_f32 v82, v90, v87
	v_cvt_pk_bf16_f32 v83, v103, v91
	v_cvt_pk_bf16_f32 v84, v92, v84
	v_cvt_pk_bf16_f32 v85, v104, v85
	global_store_dwordx4 v[88:89], v[82:85], off
	global_load_dwordx4 v[82:85], v[94:95], off offset:256
	s_waitcnt vmcnt(0)
	v_lshlrev_b32_e32 v87, 16, v82
	v_fma_f32 v78, v38, v87, v78
	v_mul_f32_e32 v87, 0x3d372713, v78
	v_mul_f32_e32 v87, v78, v87
	v_fma_f32 v87, v78, v87, v78
	v_mul_f32_e32 v87, 0x3f4c422a, v87
	v_mul_f32_e64 v88, |v87|, s76
	v_add_f32_e32 v88, v88, v88
	v_exp_f32_e32 v88, v88
	s_nop 0
	v_add_f32_e32 v88, 1.0, v88
	v_rcp_f32_e32 v88, v88
	s_nop 0
	v_fma_f32 v88, v88, -2.0, 1.0
	v_lshlrev_b32_e32 v89, 16, v84
	v_fma_f32 v74, v26, v89, v74
	v_mul_f32_e32 v89, 0x3d372713, v74
	v_mul_f32_e32 v89, v74, v89
	v_fma_f32 v89, v74, v89, v74
	v_mul_f32_e32 v89, 0x3f4c422a, v89
	v_mul_f32_e64 v90, |v89|, s76
	v_add_f32_e32 v90, v90, v90
	v_exp_f32_e32 v90, v90
	s_nop 0
	v_add_f32_e32 v90, 1.0, v90
	v_rcp_f32_e32 v90, v90
	s_nop 0
	v_fma_f32 v90, v90, -2.0, 1.0
	v_and_b32_e32 v82, 0xffff0000, v82
	v_fma_f32 v82, v39, v82, v79
	v_mul_f32_e32 v79, 0x3d372713, v82
	v_mul_f32_e32 v79, v82, v79
	v_fma_f32 v79, v82, v79, v82
	v_mul_f32_e32 v79, 0x3f4c422a, v79
	v_mul_f32_e64 v91, |v79|, s76
	v_add_f32_e32 v91, v91, v91
	v_exp_f32_e32 v91, v91
	s_nop 0
	v_add_f32_e32 v91, 1.0, v91
	v_rcp_f32_e32 v91, v91
	s_nop 0
	v_fma_f32 v91, v91, -2.0, 1.0
	v_and_b32_e32 v84, 0xffff0000, v84
	v_fma_f32 v84, v27, v84, v75
	v_mul_f32_e32 v75, 0x3d372713, v84
	v_mul_f32_e32 v75, v84, v75
	v_fma_f32 v75, v84, v75, v84
	v_mul_f32_e32 v75, 0x3f4c422a, v75
	v_mul_f32_e64 v92, |v75|, s76
	v_add_f32_e32 v92, v92, v92
	v_exp_f32_e32 v92, v92
	s_nop 0
	v_add_f32_e32 v92, 1.0, v92
	v_rcp_f32_e32 v92, v92
	s_nop 0
	v_fma_f32 v92, v92, -2.0, 1.0
	v_lshlrev_b32_e32 v93, 16, v83
	v_fma_f32 v80, v40, v93, v80
	v_mul_f32_e32 v93, 0x3d372713, v80
	v_mul_f32_e32 v93, v80, v93
	v_fma_f32 v93, v80, v93, v80
	v_mul_f32_e32 v93, 0x3f4c422a, v93
	v_mul_f32_e64 v94, |v93|, s76
	v_add_f32_e32 v94, v94, v94
	v_exp_f32_e32 v94, v94
	s_nop 0
	v_add_f32_e32 v94, 1.0, v94
	v_rcp_f32_e32 v94, v94
	s_nop 0
	v_fma_f32 v94, v94, -2.0, 1.0
	v_lshlrev_b32_e32 v95, 16, v85
	v_fma_f32 v76, v28, v95, v76
	v_mul_f32_e32 v95, 0x3d372713, v76
	v_mul_f32_e32 v95, v76, v95
	v_fma_f32 v95, v76, v95, v76
	v_mul_f32_e32 v95, 0x3f4c422a, v95
	v_mul_f32_e64 v96, |v95|, s76
	v_add_f32_e32 v96, v96, v96
	v_exp_f32_e32 v96, v96
	s_nop 0
	v_add_f32_e32 v96, 1.0, v96
	v_rcp_f32_e32 v96, v96
	s_nop 0
	v_fma_f32 v96, v96, -2.0, 1.0
	v_and_b32_e32 v83, 0xffff0000, v83
	v_fmac_f32_e32 v81, v41, v83
	v_mul_f32_e32 v83, 0x3d372713, v81
	v_mul_f32_e32 v83, v81, v83
	v_fma_f32 v83, v81, v83, v81
	v_mul_f32_e32 v83, 0x3f4c422a, v83
	v_mul_f32_e64 v97, |v83|, s76
	v_add_f32_e32 v97, v97, v97
	v_exp_f32_e32 v97, v97
	s_nop 0
	v_add_f32_e32 v97, 1.0, v97
	v_rcp_f32_e32 v97, v97
	s_nop 0
	v_fma_f32 v97, v97, -2.0, 1.0
	v_and_b32_e32 v85, 0xffff0000, v85
	v_fmac_f32_e32 v77, v29, v85
	v_mul_f32_e32 v85, 0x3d372713, v77
	v_mul_f32_e32 v85, v77, v85
	v_fma_f32 v85, v77, v85, v77
	v_mul_f32_e32 v85, 0x3f4c422a, v85
	v_mul_f32_e64 v98, |v85|, s76
	v_add_f32_e32 v98, v98, v98
	v_exp_f32_e32 v98, v98
	s_nop 0
	v_add_f32_e32 v98, 1.0, v98
	v_rcp_f32_e32 v98, v98
	s_nop 0
	v_fma_f32 v98, v98, -2.0, 1.0
	v_bfi_b32 v83, s10, v97, v83
	v_mul_f32_e32 v81, 0.5, v81
	v_add_f32_e32 v83, 1.0, v83
	v_mul_f32_e32 v81, v81, v83
	v_bfi_b32 v83, s10, v96, v95
	v_mul_f32_e32 v76, 0.5, v76
	v_add_f32_e32 v83, 1.0, v83
	v_mul_f32_e32 v83, v76, v83
	v_mul_f32_e32 v76, 0.5, v84
	v_bfi_b32 v84, s10, v90, v89
	v_mul_f32_e32 v74, 0.5, v74
	v_add_f32_e32 v84, 1.0, v84
	v_mul_f32_e32 v84, v74, v84
	v_bfi_b32 v74, s10, v92, v75
	v_mul_f32_e32 v75, 0.5, v78
	v_bfi_b32 v78, s10, v88, v87
	v_add_f32_e32 v74, 1.0, v74
	v_add_f32_e32 v78, 1.0, v78
	v_mul_f32_e32 v76, v76, v74
	v_mul_f32_e32 v74, 0.5, v82
	v_mul_f32_e32 v82, v75, v78
	v_bfi_b32 v75, s10, v91, v79
	v_add_f32_e32 v75, 1.0, v75
	v_mul_f32_e32 v87, v74, v75
	v_bfi_b32 v74, s10, v98, v85
	v_mul_f32_e32 v77, 0.5, v77
	v_add_f32_e32 v74, 1.0, v74
	v_bfi_b32 v93, s10, v94, v93
	v_mul_f32_e32 v77, v77, v74
	v_or_b32_e32 v74, v86, v130
	v_mul_f32_e32 v80, 0.5, v80
	v_add_f32_e32 v93, 1.0, v93
	v_ashrrev_i32_e32 v75, 31, v74
	v_mul_f32_e32 v80, v80, v93
	v_lshlrev_b64 v[74:75], 10, v[74:75]
	v_lshl_add_u64 v[78:79], v[134:135], 0, v[74:75]
	v_cvt_pk_bf16_f32 v75, v80, v81
	v_add_u32_e32 v80, 0x80, v142
	v_cvt_pk_bf16_f32 v74, v82, v87
	v_cvt_pk_bf16_f32 v76, v84, v76
	v_cvt_pk_bf16_f32 v77, v83, v77
	v_ashrrev_i32_e32 v81, 31, v80
	global_store_dwordx4 v[78:79], v[74:77], off
	s_nop 1
	v_lshlrev_b64 v[74:75], 9, v[80:81]
	v_lshl_add_u64 v[74:75], s[0:1], 0, v[74:75]
	v_lshl_add_u64 v[78:79], v[74:75], 0, v[0:1]
	global_load_dwordx4 v[74:77], v[78:79], off
	s_waitcnt vmcnt(0)
	v_lshlrev_b32_e32 v81, 16, v74
	v_fma_f32 v70, v38, v81, v70
	v_mul_f32_e32 v81, 0x3d372713, v70
	v_mul_f32_e32 v81, v70, v81
	v_fma_f32 v81, v70, v81, v70
	v_mul_f32_e32 v81, 0x3f4c422a, v81
	v_mul_f32_e64 v82, |v81|, s76
	v_add_f32_e32 v82, v82, v82
	v_exp_f32_e32 v82, v82
	s_nop 0
	v_add_f32_e32 v82, 1.0, v82
	v_rcp_f32_e32 v82, v82
	s_nop 0
	v_fma_f32 v82, v82, -2.0, 1.0
	v_lshlrev_b32_e32 v83, 16, v76
	v_fma_f32 v66, v26, v83, v66
	v_mul_f32_e32 v83, 0x3d372713, v66
	v_mul_f32_e32 v83, v66, v83
	v_fma_f32 v83, v66, v83, v66
	v_mul_f32_e32 v83, 0x3f4c422a, v83
	v_mul_f32_e64 v84, |v83|, s76
	v_add_f32_e32 v84, v84, v84
	v_exp_f32_e32 v84, v84
	s_nop 0
	v_add_f32_e32 v84, 1.0, v84
	v_rcp_f32_e32 v84, v84
	s_nop 0
	v_fma_f32 v84, v84, -2.0, 1.0
	v_and_b32_e32 v74, 0xffff0000, v74
	v_fma_f32 v74, v39, v74, v71
	v_mul_f32_e32 v71, 0x3d372713, v74
	v_mul_f32_e32 v71, v74, v71
	v_fma_f32 v71, v74, v71, v74
	v_mul_f32_e32 v71, 0x3f4c422a, v71
	v_mul_f32_e64 v85, |v71|, s76
	v_add_f32_e32 v85, v85, v85
	v_exp_f32_e32 v85, v85
	s_nop 0
	v_add_f32_e32 v85, 1.0, v85
	v_rcp_f32_e32 v85, v85
	s_nop 0
	v_fma_f32 v85, v85, -2.0, 1.0
	v_and_b32_e32 v76, 0xffff0000, v76
	v_fma_f32 v76, v27, v76, v67
	v_mul_f32_e32 v67, 0x3d372713, v76
	v_mul_f32_e32 v67, v76, v67
	v_fma_f32 v67, v76, v67, v76
	v_mul_f32_e32 v67, 0x3f4c422a, v67
	v_mul_f32_e64 v86, |v67|, s76
	v_add_f32_e32 v86, v86, v86
	v_exp_f32_e32 v86, v86
	s_nop 0
	v_add_f32_e32 v86, 1.0, v86
	v_rcp_f32_e32 v86, v86
	s_nop 0
	v_fma_f32 v86, v86, -2.0, 1.0
	v_lshlrev_b32_e32 v87, 16, v75
	v_fma_f32 v72, v40, v87, v72
	v_mul_f32_e32 v87, 0x3d372713, v72
	v_mul_f32_e32 v87, v72, v87
	v_fma_f32 v87, v72, v87, v72
	v_mul_f32_e32 v87, 0x3f4c422a, v87
	v_mul_f32_e64 v88, |v87|, s76
	v_add_f32_e32 v88, v88, v88
	v_exp_f32_e32 v88, v88
	s_nop 0
	v_add_f32_e32 v88, 1.0, v88
	v_rcp_f32_e32 v88, v88
	s_nop 0
	v_fma_f32 v88, v88, -2.0, 1.0
	v_lshlrev_b32_e32 v89, 16, v77
	v_fma_f32 v68, v28, v89, v68
	v_mul_f32_e32 v89, 0x3d372713, v68
	v_mul_f32_e32 v89, v68, v89
	v_fma_f32 v89, v68, v89, v68
	v_mul_f32_e32 v89, 0x3f4c422a, v89
	v_mul_f32_e64 v90, |v89|, s76
	v_add_f32_e32 v90, v90, v90
	v_exp_f32_e32 v90, v90
	s_nop 0
	v_add_f32_e32 v90, 1.0, v90
	v_rcp_f32_e32 v90, v90
	s_nop 0
	v_fma_f32 v90, v90, -2.0, 1.0
	v_and_b32_e32 v75, 0xffff0000, v75
	v_fmac_f32_e32 v73, v41, v75
	v_mul_f32_e32 v75, 0x3d372713, v73
	v_mul_f32_e32 v75, v73, v75
	v_fma_f32 v75, v73, v75, v73
	v_mul_f32_e32 v75, 0x3f4c422a, v75
	v_mul_f32_e64 v91, |v75|, s76
	v_add_f32_e32 v91, v91, v91
	v_exp_f32_e32 v91, v91
	s_nop 0
	v_add_f32_e32 v91, 1.0, v91
	v_rcp_f32_e32 v91, v91
	s_nop 0
	v_fma_f32 v91, v91, -2.0, 1.0
	v_and_b32_e32 v77, 0xffff0000, v77
	v_fmac_f32_e32 v69, v29, v77
	v_mul_f32_e32 v77, 0x3d372713, v69
	v_mul_f32_e32 v77, v69, v77
	v_fma_f32 v77, v69, v77, v69
	v_mul_f32_e32 v77, 0x3f4c422a, v77
	v_mul_f32_e64 v92, |v77|, s76
	v_add_f32_e32 v92, v92, v92
	v_exp_f32_e32 v92, v92
	s_nop 0
	v_add_f32_e32 v92, 1.0, v92
	v_rcp_f32_e32 v92, v92
	s_nop 0
	v_fma_f32 v92, v92, -2.0, 1.0
	v_bfi_b32 v87, s10, v88, v87
	v_mul_f32_e32 v72, 0.5, v72
	v_add_f32_e32 v87, 1.0, v87
	v_mul_f32_e32 v87, v72, v87
	v_bfi_b32 v72, s10, v91, v75
	v_mul_f32_e32 v73, 0.5, v73
	v_add_f32_e32 v72, 1.0, v72
	v_mul_f32_e32 v75, v73, v72
	v_bfi_b32 v72, s10, v90, v89
	v_mul_f32_e32 v68, 0.5, v68
	v_add_f32_e32 v72, 1.0, v72
	v_mul_f32_e32 v88, v68, v72
	v_bfi_b32 v72, s10, v84, v83
	v_mul_f32_e32 v66, 0.5, v66
	v_add_f32_e32 v72, 1.0, v72
	v_mul_f32_e32 v68, 0.5, v76
	v_mul_f32_e32 v76, v66, v72
	v_bfi_b32 v66, s10, v86, v67
	v_mul_f32_e32 v67, 0.5, v70
	v_bfi_b32 v70, s10, v82, v81
	v_add_f32_e32 v66, 1.0, v66
	v_add_f32_e32 v70, 1.0, v70
	v_mul_f32_e32 v68, v68, v66
	v_mul_f32_e32 v66, 0.5, v74
	v_mul_f32_e32 v74, v67, v70
	v_bfi_b32 v67, s10, v85, v71
	v_add_f32_e32 v67, 1.0, v67
	v_mul_f32_e32 v71, v66, v67
	v_bfi_b32 v66, s10, v92, v77
	v_mul_f32_e32 v69, 0.5, v69
	v_lshlrev_b32_e32 v70, 4, v80
	v_add_f32_e32 v66, 1.0, v66
	v_mul_f32_e32 v69, v69, v66
	v_or_b32_e32 v66, v70, v136
	v_ashrrev_i32_e32 v67, 31, v66
	v_lshlrev_b64 v[66:67], 10, v[66:67]
	v_lshl_add_u64 v[72:73], v[134:135], 0, v[66:67]
	v_cvt_pk_bf16_f32 v66, v74, v71
	v_cvt_pk_bf16_f32 v67, v87, v75
	v_cvt_pk_bf16_f32 v68, v76, v68
	v_cvt_pk_bf16_f32 v69, v88, v69
	global_store_dwordx4 v[72:73], v[66:69], off
	global_load_dwordx4 v[66:69], v[78:79], off offset:256
	s_waitcnt vmcnt(0)
	v_lshlrev_b32_e32 v71, 16, v66
	v_fma_f32 v62, v38, v71, v62
	v_mul_f32_e32 v71, 0x3d372713, v62
	v_mul_f32_e32 v71, v62, v71
	v_fma_f32 v71, v62, v71, v62
	v_mul_f32_e32 v71, 0x3f4c422a, v71
	v_mul_f32_e64 v72, |v71|, s76
	v_add_f32_e32 v72, v72, v72
	v_exp_f32_e32 v72, v72
	s_nop 0
	v_add_f32_e32 v72, 1.0, v72
	v_rcp_f32_e32 v72, v72
	s_nop 0
	v_fma_f32 v72, v72, -2.0, 1.0
	v_lshlrev_b32_e32 v73, 16, v68
	v_fma_f32 v58, v26, v73, v58
	v_mul_f32_e32 v73, 0x3d372713, v58
	v_mul_f32_e32 v73, v58, v73
	v_fma_f32 v73, v58, v73, v58
	v_mul_f32_e32 v73, 0x3f4c422a, v73
	v_mul_f32_e64 v74, |v73|, s76
	v_add_f32_e32 v74, v74, v74
	v_exp_f32_e32 v74, v74
	s_nop 0
	v_add_f32_e32 v74, 1.0, v74
	v_rcp_f32_e32 v74, v74
	s_nop 0
	v_fma_f32 v74, v74, -2.0, 1.0
	v_and_b32_e32 v66, 0xffff0000, v66
	v_fma_f32 v66, v39, v66, v63
	v_mul_f32_e32 v63, 0x3d372713, v66
	v_mul_f32_e32 v63, v66, v63
	v_fma_f32 v63, v66, v63, v66
	v_mul_f32_e32 v63, 0x3f4c422a, v63
	v_mul_f32_e64 v75, |v63|, s76
	v_add_f32_e32 v75, v75, v75
	v_exp_f32_e32 v75, v75
	s_nop 0
	v_add_f32_e32 v75, 1.0, v75
	v_rcp_f32_e32 v75, v75
	s_nop 0
	v_fma_f32 v75, v75, -2.0, 1.0
	v_and_b32_e32 v68, 0xffff0000, v68
	v_fma_f32 v68, v27, v68, v59
	v_mul_f32_e32 v59, 0x3d372713, v68
	v_mul_f32_e32 v59, v68, v59
	v_fma_f32 v59, v68, v59, v68
	v_mul_f32_e32 v59, 0x3f4c422a, v59
	v_mul_f32_e64 v76, |v59|, s76
	v_add_f32_e32 v76, v76, v76
	v_exp_f32_e32 v76, v76
	s_nop 0
	v_add_f32_e32 v76, 1.0, v76
	v_rcp_f32_e32 v76, v76
	s_nop 0
	v_fma_f32 v76, v76, -2.0, 1.0
	v_lshlrev_b32_e32 v77, 16, v67
	v_fma_f32 v64, v40, v77, v64
	v_mul_f32_e32 v77, 0x3d372713, v64
	v_mul_f32_e32 v77, v64, v77
	v_fma_f32 v77, v64, v77, v64
	v_mul_f32_e32 v77, 0x3f4c422a, v77
	v_mul_f32_e64 v78, |v77|, s76
	v_add_f32_e32 v78, v78, v78
	v_exp_f32_e32 v78, v78
	s_nop 0
	v_add_f32_e32 v78, 1.0, v78
	v_rcp_f32_e32 v78, v78
	s_nop 0
	v_fma_f32 v78, v78, -2.0, 1.0
	v_lshlrev_b32_e32 v79, 16, v69
	v_fma_f32 v60, v28, v79, v60
	v_mul_f32_e32 v79, 0x3d372713, v60
	v_mul_f32_e32 v79, v60, v79
	v_fma_f32 v79, v60, v79, v60
	v_mul_f32_e32 v79, 0x3f4c422a, v79
	v_mul_f32_e64 v80, |v79|, s76
	v_add_f32_e32 v80, v80, v80
	v_exp_f32_e32 v80, v80
	s_nop 0
	v_add_f32_e32 v80, 1.0, v80
	v_rcp_f32_e32 v80, v80
	s_nop 0
	v_fma_f32 v80, v80, -2.0, 1.0
	v_and_b32_e32 v67, 0xffff0000, v67
	v_fmac_f32_e32 v65, v41, v67
	v_mul_f32_e32 v67, 0x3d372713, v65
	v_mul_f32_e32 v67, v65, v67
	v_fma_f32 v67, v65, v67, v65
	v_mul_f32_e32 v67, 0x3f4c422a, v67
	v_mul_f32_e64 v81, |v67|, s76
	v_add_f32_e32 v81, v81, v81
	v_exp_f32_e32 v81, v81
	s_nop 0
	v_add_f32_e32 v81, 1.0, v81
	v_rcp_f32_e32 v81, v81
	s_nop 0
	v_fma_f32 v81, v81, -2.0, 1.0
	v_and_b32_e32 v69, 0xffff0000, v69
	v_fmac_f32_e32 v61, v29, v69
	v_mul_f32_e32 v69, 0x3d372713, v61
	v_mul_f32_e32 v69, v61, v69
	v_fma_f32 v69, v61, v69, v61
	v_mul_f32_e32 v69, 0x3f4c422a, v69
	v_mul_f32_e64 v82, |v69|, s76
	v_add_f32_e32 v82, v82, v82
	v_exp_f32_e32 v82, v82
	s_nop 0
	v_add_f32_e32 v82, 1.0, v82
	v_rcp_f32_e32 v82, v82
	s_nop 0
	v_fma_f32 v82, v82, -2.0, 1.0
	v_bfi_b32 v67, s10, v81, v67
	v_mul_f32_e32 v65, 0.5, v65
	v_add_f32_e32 v67, 1.0, v67
	v_mul_f32_e32 v65, v65, v67
	v_bfi_b32 v67, s10, v80, v79
	v_mul_f32_e32 v60, 0.5, v60
	v_add_f32_e32 v67, 1.0, v67
	v_mul_f32_e32 v67, v60, v67
	v_mul_f32_e32 v60, 0.5, v68
	v_bfi_b32 v68, s10, v74, v73
	v_mul_f32_e32 v58, 0.5, v58
	v_add_f32_e32 v68, 1.0, v68
	v_mul_f32_e32 v68, v58, v68
	v_bfi_b32 v58, s10, v76, v59
	v_mul_f32_e32 v59, 0.5, v62
	v_bfi_b32 v62, s10, v72, v71
	v_add_f32_e32 v58, 1.0, v58
	v_add_f32_e32 v62, 1.0, v62
	v_mul_f32_e32 v60, v60, v58
	v_mul_f32_e32 v58, 0.5, v66
	v_mul_f32_e32 v66, v59, v62
	v_bfi_b32 v59, s10, v75, v63
	v_add_f32_e32 v59, 1.0, v59
	v_mul_f32_e32 v71, v58, v59
	v_bfi_b32 v58, s10, v82, v69
	v_mul_f32_e32 v61, 0.5, v61
	v_add_f32_e32 v58, 1.0, v58
	v_bfi_b32 v77, s10, v78, v77
	v_mul_f32_e32 v61, v61, v58
	v_or_b32_e32 v58, v70, v130
	v_mul_f32_e32 v64, 0.5, v64
	v_add_f32_e32 v77, 1.0, v77
	v_ashrrev_i32_e32 v59, 31, v58
	v_mul_f32_e32 v64, v64, v77
	v_lshlrev_b64 v[58:59], 10, v[58:59]
	v_lshl_add_u64 v[62:63], v[134:135], 0, v[58:59]
	v_cvt_pk_bf16_f32 v59, v64, v65
	v_add_u32_e32 v64, 0x90, v142
	v_cvt_pk_bf16_f32 v58, v66, v71
	v_cvt_pk_bf16_f32 v60, v68, v60
	v_cvt_pk_bf16_f32 v61, v67, v61
	v_ashrrev_i32_e32 v65, 31, v64
	global_store_dwordx4 v[62:63], v[58:61], off
	s_nop 1
	v_lshlrev_b64 v[58:59], 9, v[64:65]
	v_lshl_add_u64 v[58:59], s[0:1], 0, v[58:59]
	v_lshl_add_u64 v[62:63], v[58:59], 0, v[0:1]
	global_load_dwordx4 v[58:61], v[62:63], off
	s_waitcnt vmcnt(0)
	v_lshlrev_b32_e32 v65, 16, v58
	v_fma_f32 v54, v38, v65, v54
	v_mul_f32_e32 v65, 0x3d372713, v54
	v_mul_f32_e32 v65, v54, v65
	v_fma_f32 v65, v54, v65, v54
	v_mul_f32_e32 v65, 0x3f4c422a, v65
	v_mul_f32_e64 v66, |v65|, s76
	v_add_f32_e32 v66, v66, v66
	v_exp_f32_e32 v66, v66
	s_nop 0
	v_add_f32_e32 v66, 1.0, v66
	v_rcp_f32_e32 v66, v66
	s_nop 0
	v_fma_f32 v66, v66, -2.0, 1.0
	v_lshlrev_b32_e32 v67, 16, v60
	v_fma_f32 v50, v26, v67, v50
	v_mul_f32_e32 v67, 0x3d372713, v50
	v_mul_f32_e32 v67, v50, v67
	v_fma_f32 v67, v50, v67, v50
	v_mul_f32_e32 v67, 0x3f4c422a, v67
	v_mul_f32_e64 v68, |v67|, s76
	v_add_f32_e32 v68, v68, v68
	v_exp_f32_e32 v68, v68
	s_nop 0
	v_add_f32_e32 v68, 1.0, v68
	v_rcp_f32_e32 v68, v68
	s_nop 0
	v_fma_f32 v68, v68, -2.0, 1.0
	v_and_b32_e32 v58, 0xffff0000, v58
	v_fma_f32 v58, v39, v58, v55
	v_mul_f32_e32 v55, 0x3d372713, v58
	v_mul_f32_e32 v55, v58, v55
	v_fma_f32 v55, v58, v55, v58
	v_mul_f32_e32 v55, 0x3f4c422a, v55
	v_mul_f32_e64 v69, |v55|, s76
	v_add_f32_e32 v69, v69, v69
	v_exp_f32_e32 v69, v69
	s_nop 0
	v_add_f32_e32 v69, 1.0, v69
	v_rcp_f32_e32 v69, v69
	s_nop 0
	v_fma_f32 v69, v69, -2.0, 1.0
	v_and_b32_e32 v60, 0xffff0000, v60
	v_fma_f32 v60, v27, v60, v51
	v_mul_f32_e32 v51, 0x3d372713, v60
	v_mul_f32_e32 v51, v60, v51
	v_fma_f32 v51, v60, v51, v60
	v_mul_f32_e32 v51, 0x3f4c422a, v51
	v_mul_f32_e64 v70, |v51|, s76
	v_add_f32_e32 v70, v70, v70
	v_exp_f32_e32 v70, v70
	s_nop 0
	v_add_f32_e32 v70, 1.0, v70
	v_rcp_f32_e32 v70, v70
	s_nop 0
	v_fma_f32 v70, v70, -2.0, 1.0
	v_lshlrev_b32_e32 v71, 16, v59
	v_fma_f32 v56, v40, v71, v56
	v_mul_f32_e32 v71, 0x3d372713, v56
	v_mul_f32_e32 v71, v56, v71
	v_fma_f32 v71, v56, v71, v56
	v_mul_f32_e32 v71, 0x3f4c422a, v71
	v_mul_f32_e64 v72, |v71|, s76
	v_add_f32_e32 v72, v72, v72
	v_exp_f32_e32 v72, v72
	s_nop 0
	v_add_f32_e32 v72, 1.0, v72
	v_rcp_f32_e32 v72, v72
	s_nop 0
	v_fma_f32 v72, v72, -2.0, 1.0
	v_lshlrev_b32_e32 v73, 16, v61
	v_fma_f32 v52, v28, v73, v52
	v_mul_f32_e32 v73, 0x3d372713, v52
	v_mul_f32_e32 v73, v52, v73
	v_fma_f32 v73, v52, v73, v52
	v_mul_f32_e32 v73, 0x3f4c422a, v73
	v_mul_f32_e64 v74, |v73|, s76
	v_add_f32_e32 v74, v74, v74
	v_exp_f32_e32 v74, v74
	s_nop 0
	v_add_f32_e32 v74, 1.0, v74
	v_rcp_f32_e32 v74, v74
	s_nop 0
	v_fma_f32 v74, v74, -2.0, 1.0
	v_and_b32_e32 v59, 0xffff0000, v59
	v_fmac_f32_e32 v57, v41, v59
	v_mul_f32_e32 v59, 0x3d372713, v57
	v_mul_f32_e32 v59, v57, v59
	v_fma_f32 v59, v57, v59, v57
	v_mul_f32_e32 v59, 0x3f4c422a, v59
	v_mul_f32_e64 v75, |v59|, s76
	v_add_f32_e32 v75, v75, v75
	v_exp_f32_e32 v75, v75
	s_nop 0
	v_add_f32_e32 v75, 1.0, v75
	v_rcp_f32_e32 v75, v75
	s_nop 0
	v_fma_f32 v75, v75, -2.0, 1.0
	v_and_b32_e32 v61, 0xffff0000, v61
	v_fmac_f32_e32 v53, v29, v61
	v_mul_f32_e32 v61, 0x3d372713, v53
	v_mul_f32_e32 v61, v53, v61
	v_fma_f32 v61, v53, v61, v53
	v_mul_f32_e32 v61, 0x3f4c422a, v61
	v_mul_f32_e64 v76, |v61|, s76
	v_add_f32_e32 v76, v76, v76
	v_exp_f32_e32 v76, v76
	s_nop 0
	v_add_f32_e32 v76, 1.0, v76
	v_rcp_f32_e32 v76, v76
	s_nop 0
	v_fma_f32 v76, v76, -2.0, 1.0
	v_bfi_b32 v71, s10, v72, v71
	v_mul_f32_e32 v56, 0.5, v56
	v_add_f32_e32 v71, 1.0, v71
	v_mul_f32_e32 v71, v56, v71
	v_bfi_b32 v56, s10, v75, v59
	v_mul_f32_e32 v57, 0.5, v57
	v_add_f32_e32 v56, 1.0, v56
	v_mul_f32_e32 v59, v57, v56
	v_bfi_b32 v56, s10, v74, v73
	v_mul_f32_e32 v52, 0.5, v52
	v_add_f32_e32 v56, 1.0, v56
	v_mul_f32_e32 v72, v52, v56
	v_bfi_b32 v56, s10, v68, v67
	v_mul_f32_e32 v50, 0.5, v50
	v_add_f32_e32 v56, 1.0, v56
	v_mul_f32_e32 v52, 0.5, v60
	v_mul_f32_e32 v60, v50, v56
	v_bfi_b32 v50, s10, v70, v51
	v_mul_f32_e32 v51, 0.5, v54
	v_bfi_b32 v54, s10, v66, v65
	v_add_f32_e32 v50, 1.0, v50
	v_add_f32_e32 v54, 1.0, v54
	v_mul_f32_e32 v52, v52, v50
	v_mul_f32_e32 v50, 0.5, v58
	v_mul_f32_e32 v58, v51, v54
	v_bfi_b32 v51, s10, v69, v55
	v_add_f32_e32 v51, 1.0, v51
	v_mul_f32_e32 v55, v50, v51
	v_bfi_b32 v50, s10, v76, v61
	v_mul_f32_e32 v53, 0.5, v53
	v_lshlrev_b32_e32 v54, 4, v64
	v_add_f32_e32 v50, 1.0, v50
	v_mul_f32_e32 v53, v53, v50
	v_or_b32_e32 v50, v54, v136
	v_ashrrev_i32_e32 v51, 31, v50
	v_lshlrev_b64 v[50:51], 10, v[50:51]
	v_lshl_add_u64 v[56:57], v[134:135], 0, v[50:51]
	v_cvt_pk_bf16_f32 v50, v58, v55
	v_cvt_pk_bf16_f32 v51, v71, v59
	v_cvt_pk_bf16_f32 v52, v60, v52
	v_cvt_pk_bf16_f32 v53, v72, v53
	global_store_dwordx4 v[56:57], v[50:53], off
	global_load_dwordx4 v[50:53], v[62:63], off offset:256
	s_waitcnt vmcnt(0)
	v_lshlrev_b32_e32 v55, 16, v50
	v_fma_f32 v46, v38, v55, v46
	v_mul_f32_e32 v55, 0x3d372713, v46
	v_mul_f32_e32 v55, v46, v55
	v_fma_f32 v55, v46, v55, v46
	v_mul_f32_e32 v55, 0x3f4c422a, v55
	v_mul_f32_e64 v56, |v55|, s76
	v_add_f32_e32 v56, v56, v56
	v_exp_f32_e32 v56, v56
	s_nop 0
	v_add_f32_e32 v56, 1.0, v56
	v_rcp_f32_e32 v56, v56
	s_nop 0
	v_fma_f32 v56, v56, -2.0, 1.0
	v_lshlrev_b32_e32 v57, 16, v52
	v_fma_f32 v42, v26, v57, v42
	v_mul_f32_e32 v57, 0x3d372713, v42
	v_mul_f32_e32 v57, v42, v57
	v_fma_f32 v57, v42, v57, v42
	v_mul_f32_e32 v57, 0x3f4c422a, v57
	v_mul_f32_e64 v58, |v57|, s76
	v_add_f32_e32 v58, v58, v58
	v_exp_f32_e32 v58, v58
	s_nop 0
	v_add_f32_e32 v58, 1.0, v58
	v_rcp_f32_e32 v58, v58
	s_nop 0
	v_fma_f32 v58, v58, -2.0, 1.0
	v_and_b32_e32 v50, 0xffff0000, v50
	v_fma_f32 v50, v39, v50, v47
	v_mul_f32_e32 v47, 0x3d372713, v50
	v_mul_f32_e32 v47, v50, v47
	v_fma_f32 v47, v50, v47, v50
	v_mul_f32_e32 v47, 0x3f4c422a, v47
	v_mul_f32_e64 v59, |v47|, s76
	v_add_f32_e32 v59, v59, v59
	v_exp_f32_e32 v59, v59
	s_nop 0
	v_add_f32_e32 v59, 1.0, v59
	v_rcp_f32_e32 v59, v59
	s_nop 0
	v_fma_f32 v59, v59, -2.0, 1.0
	v_and_b32_e32 v52, 0xffff0000, v52
	v_fma_f32 v52, v27, v52, v43
	v_mul_f32_e32 v43, 0x3d372713, v52
	v_mul_f32_e32 v43, v52, v43
	v_fma_f32 v43, v52, v43, v52
	v_mul_f32_e32 v43, 0x3f4c422a, v43
	v_mul_f32_e64 v60, |v43|, s76
	v_add_f32_e32 v60, v60, v60
	v_exp_f32_e32 v60, v60
	s_nop 0
	v_add_f32_e32 v60, 1.0, v60
	v_rcp_f32_e32 v60, v60
	s_nop 0
	v_fma_f32 v60, v60, -2.0, 1.0
	v_lshlrev_b32_e32 v61, 16, v51
	v_fma_f32 v48, v40, v61, v48
	v_mul_f32_e32 v61, 0x3d372713, v48
	v_mul_f32_e32 v61, v48, v61
	v_fma_f32 v61, v48, v61, v48
	v_mul_f32_e32 v61, 0x3f4c422a, v61
	v_mul_f32_e64 v62, |v61|, s76
	v_add_f32_e32 v62, v62, v62
	v_exp_f32_e32 v62, v62
	s_nop 0
	v_add_f32_e32 v62, 1.0, v62
	v_rcp_f32_e32 v62, v62
	s_nop 0
	v_fma_f32 v62, v62, -2.0, 1.0
	v_lshlrev_b32_e32 v63, 16, v53
	v_fma_f32 v44, v28, v63, v44
	v_mul_f32_e32 v63, 0x3d372713, v44
	v_mul_f32_e32 v63, v44, v63
	v_fma_f32 v63, v44, v63, v44
	v_mul_f32_e32 v63, 0x3f4c422a, v63
	v_mul_f32_e64 v64, |v63|, s76
	v_add_f32_e32 v64, v64, v64
	v_exp_f32_e32 v64, v64
	s_nop 0
	v_add_f32_e32 v64, 1.0, v64
	v_rcp_f32_e32 v64, v64
	s_nop 0
	v_fma_f32 v64, v64, -2.0, 1.0
	v_and_b32_e32 v51, 0xffff0000, v51
	v_fmac_f32_e32 v49, v41, v51
	v_mul_f32_e32 v51, 0x3d372713, v49
	v_mul_f32_e32 v51, v49, v51
	v_fma_f32 v51, v49, v51, v49
	v_mul_f32_e32 v51, 0x3f4c422a, v51
	v_mul_f32_e64 v65, |v51|, s76
	v_add_f32_e32 v65, v65, v65
	v_exp_f32_e32 v65, v65
	s_nop 0
	v_add_f32_e32 v65, 1.0, v65
	v_rcp_f32_e32 v65, v65
	s_nop 0
	v_fma_f32 v65, v65, -2.0, 1.0
	v_and_b32_e32 v53, 0xffff0000, v53
	v_fmac_f32_e32 v45, v29, v53
	v_mul_f32_e32 v53, 0x3d372713, v45
	v_mul_f32_e32 v53, v45, v53
	v_fma_f32 v53, v45, v53, v45
	v_mul_f32_e32 v53, 0x3f4c422a, v53
	v_mul_f32_e64 v66, |v53|, s76
	v_add_f32_e32 v66, v66, v66
	v_exp_f32_e32 v66, v66
	s_nop 0
	v_add_f32_e32 v66, 1.0, v66
	v_rcp_f32_e32 v66, v66
	s_nop 0
	v_fma_f32 v66, v66, -2.0, 1.0
	v_bfi_b32 v51, s10, v65, v51
	v_mul_f32_e32 v49, 0.5, v49
	v_add_f32_e32 v51, 1.0, v51
	v_mul_f32_e32 v49, v49, v51
	v_bfi_b32 v51, s10, v64, v63
	v_mul_f32_e32 v44, 0.5, v44
	v_add_f32_e32 v51, 1.0, v51
	v_mul_f32_e32 v51, v44, v51
	v_mul_f32_e32 v44, 0.5, v52
	v_bfi_b32 v52, s10, v58, v57
	v_mul_f32_e32 v42, 0.5, v42
	v_add_f32_e32 v52, 1.0, v52
	v_mul_f32_e32 v52, v42, v52
	v_bfi_b32 v42, s10, v60, v43
	v_mul_f32_e32 v43, 0.5, v46
	v_bfi_b32 v46, s10, v56, v55
	v_add_f32_e32 v42, 1.0, v42
	v_add_f32_e32 v46, 1.0, v46
	v_mul_f32_e32 v44, v44, v42
	v_mul_f32_e32 v42, 0.5, v50
	v_mul_f32_e32 v50, v43, v46
	v_bfi_b32 v43, s10, v59, v47
	v_add_f32_e32 v43, 1.0, v43
	v_mul_f32_e32 v55, v42, v43
	v_bfi_b32 v42, s10, v66, v53
	v_mul_f32_e32 v45, 0.5, v45
	v_add_f32_e32 v42, 1.0, v42
	v_bfi_b32 v61, s10, v62, v61
	v_mul_f32_e32 v45, v45, v42
	v_or_b32_e32 v42, v54, v130
	v_mul_f32_e32 v48, 0.5, v48
	v_add_f32_e32 v61, 1.0, v61
	v_ashrrev_i32_e32 v43, 31, v42
	v_mul_f32_e32 v48, v48, v61
	v_lshlrev_b64 v[42:43], 10, v[42:43]
	v_lshl_add_u64 v[46:47], v[134:135], 0, v[42:43]
	v_cvt_pk_bf16_f32 v43, v48, v49
	v_add_u32_e32 v48, 0xa0, v142
	v_cvt_pk_bf16_f32 v42, v50, v55
	v_cvt_pk_bf16_f32 v44, v52, v44
	v_cvt_pk_bf16_f32 v45, v51, v45
	v_ashrrev_i32_e32 v49, 31, v48
	global_store_dwordx4 v[46:47], v[42:45], off
	s_nop 1
	v_lshlrev_b64 v[42:43], 9, v[48:49]
	v_lshl_add_u64 v[42:43], s[0:1], 0, v[42:43]
	v_lshl_add_u64 v[46:47], v[42:43], 0, v[0:1]
	global_load_dwordx4 v[42:45], v[46:47], off
	s_waitcnt vmcnt(0)
	v_lshlrev_b32_e32 v49, 16, v42
	v_fma_f32 v34, v38, v49, v34
	v_mul_f32_e32 v49, 0x3d372713, v34
	v_mul_f32_e32 v49, v34, v49
	v_fma_f32 v49, v34, v49, v34
	v_mul_f32_e32 v49, 0x3f4c422a, v49
	v_mul_f32_e64 v50, |v49|, s76
	v_add_f32_e32 v50, v50, v50
	v_exp_f32_e32 v50, v50
	s_nop 0
	v_add_f32_e32 v50, 1.0, v50
	v_rcp_f32_e32 v50, v50
	s_nop 0
	v_fma_f32 v50, v50, -2.0, 1.0
	v_lshlrev_b32_e32 v51, 16, v44
	v_fma_f32 v30, v26, v51, v30
	v_mul_f32_e32 v51, 0x3d372713, v30
	v_mul_f32_e32 v51, v30, v51
	v_fma_f32 v51, v30, v51, v30
	v_mul_f32_e32 v51, 0x3f4c422a, v51
	v_mul_f32_e64 v52, |v51|, s76
	v_add_f32_e32 v52, v52, v52
	v_exp_f32_e32 v52, v52
	s_nop 0
	v_add_f32_e32 v52, 1.0, v52
	v_rcp_f32_e32 v52, v52
	s_nop 0
	v_fma_f32 v52, v52, -2.0, 1.0
	v_and_b32_e32 v42, 0xffff0000, v42
	v_fma_f32 v42, v39, v42, v35
	v_mul_f32_e32 v35, 0x3d372713, v42
	v_mul_f32_e32 v35, v42, v35
	v_fma_f32 v35, v42, v35, v42
	v_mul_f32_e32 v35, 0x3f4c422a, v35
	v_mul_f32_e64 v53, |v35|, s76
	v_add_f32_e32 v53, v53, v53
	v_exp_f32_e32 v53, v53
	s_nop 0
	v_add_f32_e32 v53, 1.0, v53
	v_rcp_f32_e32 v53, v53
	s_nop 0
	v_fma_f32 v53, v53, -2.0, 1.0
	v_and_b32_e32 v44, 0xffff0000, v44
	v_fma_f32 v44, v27, v44, v31
	v_mul_f32_e32 v31, 0x3d372713, v44
	v_mul_f32_e32 v31, v44, v31
	v_fma_f32 v31, v44, v31, v44
	v_mul_f32_e32 v31, 0x3f4c422a, v31
	v_mul_f32_e64 v54, |v31|, s76
	v_add_f32_e32 v54, v54, v54
	v_exp_f32_e32 v54, v54
	s_nop 0
	v_add_f32_e32 v54, 1.0, v54
	v_rcp_f32_e32 v54, v54
	s_nop 0
	v_fma_f32 v54, v54, -2.0, 1.0
	v_lshlrev_b32_e32 v55, 16, v43
	v_fma_f32 v36, v40, v55, v36
	v_mul_f32_e32 v55, 0x3d372713, v36
	v_mul_f32_e32 v55, v36, v55
	v_fma_f32 v55, v36, v55, v36
	v_mul_f32_e32 v55, 0x3f4c422a, v55
	v_mul_f32_e64 v56, |v55|, s76
	v_add_f32_e32 v56, v56, v56
	v_exp_f32_e32 v56, v56
	s_nop 0
	v_add_f32_e32 v56, 1.0, v56
	v_rcp_f32_e32 v56, v56
	s_nop 0
	v_fma_f32 v56, v56, -2.0, 1.0
	v_lshlrev_b32_e32 v57, 16, v45
	v_fma_f32 v32, v28, v57, v32
	v_mul_f32_e32 v57, 0x3d372713, v32
	v_mul_f32_e32 v57, v32, v57
	v_fma_f32 v57, v32, v57, v32
	v_mul_f32_e32 v57, 0x3f4c422a, v57
	v_mul_f32_e64 v58, |v57|, s76
	v_add_f32_e32 v58, v58, v58
	v_exp_f32_e32 v58, v58
	s_nop 0
	v_add_f32_e32 v58, 1.0, v58
	v_rcp_f32_e32 v58, v58
	s_nop 0
	v_fma_f32 v58, v58, -2.0, 1.0
	v_and_b32_e32 v43, 0xffff0000, v43
	v_fmac_f32_e32 v37, v41, v43
	v_mul_f32_e32 v43, 0x3d372713, v37
	v_mul_f32_e32 v43, v37, v43
	v_fma_f32 v43, v37, v43, v37
	v_mul_f32_e32 v43, 0x3f4c422a, v43
	v_mul_f32_e64 v59, |v43|, s76
	v_add_f32_e32 v59, v59, v59
	v_exp_f32_e32 v59, v59
	s_nop 0
	v_add_f32_e32 v59, 1.0, v59
	v_rcp_f32_e32 v59, v59
	s_nop 0
	v_fma_f32 v59, v59, -2.0, 1.0
	v_and_b32_e32 v45, 0xffff0000, v45
	v_fmac_f32_e32 v33, v29, v45
	v_mul_f32_e32 v45, 0x3d372713, v33
	v_mul_f32_e32 v45, v33, v45
	v_fma_f32 v45, v33, v45, v33
	v_mul_f32_e32 v45, 0x3f4c422a, v45
	v_mul_f32_e64 v60, |v45|, s76
	v_add_f32_e32 v60, v60, v60
	v_exp_f32_e32 v60, v60
	s_nop 0
	v_add_f32_e32 v60, 1.0, v60
	v_rcp_f32_e32 v60, v60
	s_nop 0
	v_fma_f32 v60, v60, -2.0, 1.0
	v_bfi_b32 v55, s10, v56, v55
	v_mul_f32_e32 v36, 0.5, v36
	v_add_f32_e32 v55, 1.0, v55
	v_mul_f32_e32 v55, v36, v55
	v_bfi_b32 v36, s10, v59, v43
	v_mul_f32_e32 v37, 0.5, v37
	v_add_f32_e32 v36, 1.0, v36
	v_mul_f32_e32 v43, v37, v36
	v_bfi_b32 v36, s10, v58, v57
	v_mul_f32_e32 v32, 0.5, v32
	v_add_f32_e32 v36, 1.0, v36
	v_mul_f32_e32 v56, v32, v36
	v_bfi_b32 v36, s10, v52, v51
	v_mul_f32_e32 v30, 0.5, v30
	v_add_f32_e32 v36, 1.0, v36
	v_mul_f32_e32 v32, 0.5, v44
	v_mul_f32_e32 v44, v30, v36
	v_bfi_b32 v30, s10, v54, v31
	v_mul_f32_e32 v31, 0.5, v34
	v_bfi_b32 v34, s10, v50, v49
	v_add_f32_e32 v30, 1.0, v30
	v_add_f32_e32 v34, 1.0, v34
	v_mul_f32_e32 v32, v32, v30
	v_mul_f32_e32 v30, 0.5, v42
	v_mul_f32_e32 v42, v31, v34
	v_bfi_b32 v31, s10, v53, v35
	v_add_f32_e32 v31, 1.0, v31
	v_mul_f32_e32 v35, v30, v31
	v_bfi_b32 v30, s10, v60, v45
	v_mul_f32_e32 v33, 0.5, v33
	v_lshlrev_b32_e32 v34, 4, v48
	v_add_f32_e32 v30, 1.0, v30
	v_mul_f32_e32 v33, v33, v30
	v_or_b32_e32 v30, v34, v136
	v_ashrrev_i32_e32 v31, 31, v30
	v_lshlrev_b64 v[30:31], 10, v[30:31]
	v_lshl_add_u64 v[36:37], v[134:135], 0, v[30:31]
	v_cvt_pk_bf16_f32 v30, v42, v35
	v_cvt_pk_bf16_f32 v31, v55, v43
	v_cvt_pk_bf16_f32 v32, v44, v32
	v_cvt_pk_bf16_f32 v33, v56, v33
	global_store_dwordx4 v[36:37], v[30:33], off
	global_load_dwordx4 v[30:33], v[46:47], off offset:256
	s_waitcnt vmcnt(0)
	v_lshlrev_b32_e32 v35, 16, v30
	v_fma_f32 v22, v38, v35, v22
	v_mul_f32_e32 v35, 0x3d372713, v22
	v_mul_f32_e32 v35, v22, v35
	v_fma_f32 v35, v22, v35, v22
	v_mul_f32_e32 v35, 0x3f4c422a, v35
	v_mul_f32_e64 v36, |v35|, s76
	v_add_f32_e32 v36, v36, v36
	v_exp_f32_e32 v36, v36
	s_nop 0
	v_add_f32_e32 v36, 1.0, v36
	v_rcp_f32_e32 v36, v36
	s_nop 0
	v_fma_f32 v36, v36, -2.0, 1.0
	v_lshlrev_b32_e32 v37, 16, v32
	v_fma_f32 v18, v26, v37, v18
	v_mul_f32_e32 v37, 0x3d372713, v18
	v_mul_f32_e32 v37, v18, v37
	v_fma_f32 v37, v18, v37, v18
	v_mul_f32_e32 v37, 0x3f4c422a, v37
	v_mul_f32_e64 v42, |v37|, s76
	v_add_f32_e32 v42, v42, v42
	v_exp_f32_e32 v42, v42
	s_nop 0
	v_add_f32_e32 v42, 1.0, v42
	v_rcp_f32_e32 v42, v42
	s_nop 0
	v_fma_f32 v42, v42, -2.0, 1.0
	v_and_b32_e32 v30, 0xffff0000, v30
	v_fma_f32 v30, v39, v30, v23
	v_mul_f32_e32 v23, 0x3d372713, v30
	v_mul_f32_e32 v23, v30, v23
	v_fma_f32 v23, v30, v23, v30
	v_mul_f32_e32 v23, 0x3f4c422a, v23
	v_mul_f32_e64 v43, |v23|, s76
	v_add_f32_e32 v43, v43, v43
	v_exp_f32_e32 v43, v43
	s_nop 0
	v_add_f32_e32 v43, 1.0, v43
	v_rcp_f32_e32 v43, v43
	s_nop 0
	v_fma_f32 v43, v43, -2.0, 1.0
	v_and_b32_e32 v32, 0xffff0000, v32
	v_fma_f32 v32, v27, v32, v19
	v_mul_f32_e32 v19, 0x3d372713, v32
	v_mul_f32_e32 v19, v32, v19
	v_fma_f32 v19, v32, v19, v32
	v_mul_f32_e32 v19, 0x3f4c422a, v19
	v_mul_f32_e64 v44, |v19|, s76
	v_add_f32_e32 v44, v44, v44
	v_exp_f32_e32 v44, v44
	s_nop 0
	v_add_f32_e32 v44, 1.0, v44
	v_rcp_f32_e32 v44, v44
	s_nop 0
	v_fma_f32 v44, v44, -2.0, 1.0
	v_lshlrev_b32_e32 v45, 16, v31
	v_fma_f32 v24, v40, v45, v24
	v_mul_f32_e32 v45, 0x3d372713, v24
	v_mul_f32_e32 v45, v24, v45
	v_fma_f32 v45, v24, v45, v24
	v_mul_f32_e32 v45, 0x3f4c422a, v45
	v_mul_f32_e64 v46, |v45|, s76
	v_add_f32_e32 v46, v46, v46
	v_exp_f32_e32 v46, v46
	s_nop 0
	v_add_f32_e32 v46, 1.0, v46
	v_rcp_f32_e32 v46, v46
	s_nop 0
	v_fma_f32 v46, v46, -2.0, 1.0
	v_lshlrev_b32_e32 v47, 16, v33
	v_fma_f32 v20, v28, v47, v20
	v_mul_f32_e32 v47, 0x3d372713, v20
	v_mul_f32_e32 v47, v20, v47
	v_fma_f32 v47, v20, v47, v20
	v_mul_f32_e32 v47, 0x3f4c422a, v47
	v_mul_f32_e64 v48, |v47|, s76
	v_add_f32_e32 v48, v48, v48
	v_exp_f32_e32 v48, v48
	s_nop 0
	v_add_f32_e32 v48, 1.0, v48
	v_rcp_f32_e32 v48, v48
	s_nop 0
	v_fma_f32 v48, v48, -2.0, 1.0
	v_and_b32_e32 v31, 0xffff0000, v31
	v_fmac_f32_e32 v25, v41, v31
	v_mul_f32_e32 v31, 0x3d372713, v25
	v_mul_f32_e32 v31, v25, v31
	v_fma_f32 v31, v25, v31, v25
	v_mul_f32_e32 v31, 0x3f4c422a, v31
	v_mul_f32_e64 v49, |v31|, s76
	v_add_f32_e32 v49, v49, v49
	v_exp_f32_e32 v49, v49
	s_nop 0
	v_add_f32_e32 v49, 1.0, v49
	v_rcp_f32_e32 v49, v49
	s_nop 0
	v_fma_f32 v49, v49, -2.0, 1.0
	v_and_b32_e32 v33, 0xffff0000, v33
	v_fmac_f32_e32 v21, v29, v33
	v_mul_f32_e32 v33, 0x3d372713, v21
	v_mul_f32_e32 v33, v21, v33
	v_fma_f32 v33, v21, v33, v21
	v_mul_f32_e32 v33, 0x3f4c422a, v33
	v_mul_f32_e64 v50, |v33|, s76
	v_add_f32_e32 v50, v50, v50
	v_exp_f32_e32 v50, v50
	s_nop 0
	v_add_f32_e32 v50, 1.0, v50
	v_rcp_f32_e32 v50, v50
	s_nop 0
	v_fma_f32 v50, v50, -2.0, 1.0
	v_bfi_b32 v31, s10, v49, v31
	v_mul_f32_e32 v25, 0.5, v25
	v_add_f32_e32 v31, 1.0, v31
	v_mul_f32_e32 v25, v25, v31
	v_bfi_b32 v31, s10, v48, v47
	v_mul_f32_e32 v20, 0.5, v20
	v_add_f32_e32 v31, 1.0, v31
	v_mul_f32_e32 v31, v20, v31
	v_mul_f32_e32 v20, 0.5, v32
	v_bfi_b32 v32, s10, v42, v37
	v_mul_f32_e32 v18, 0.5, v18
	v_add_f32_e32 v32, 1.0, v32
	v_mul_f32_e32 v32, v18, v32
	v_bfi_b32 v18, s10, v44, v19
	v_mul_f32_e32 v19, 0.5, v22
	v_bfi_b32 v22, s10, v36, v35
	v_add_f32_e32 v18, 1.0, v18
	v_add_f32_e32 v22, 1.0, v22
	v_mul_f32_e32 v20, v20, v18
	v_mul_f32_e32 v18, 0.5, v30
	v_mul_f32_e32 v30, v19, v22
	v_bfi_b32 v19, s10, v43, v23
	v_add_f32_e32 v19, 1.0, v19
	v_mul_f32_e32 v35, v18, v19
	v_bfi_b32 v18, s10, v50, v33
	v_mul_f32_e32 v21, 0.5, v21
	v_add_f32_e32 v18, 1.0, v18
	v_bfi_b32 v45, s10, v46, v45
	v_mul_f32_e32 v21, v21, v18
	v_or_b32_e32 v18, v34, v130
	v_mul_f32_e32 v24, 0.5, v24
	v_add_f32_e32 v45, 1.0, v45
	v_ashrrev_i32_e32 v19, 31, v18
	v_mul_f32_e32 v24, v24, v45
	v_lshlrev_b64 v[18:19], 10, v[18:19]
	v_lshl_add_u64 v[22:23], v[134:135], 0, v[18:19]
	v_cvt_pk_bf16_f32 v19, v24, v25
	v_add_u32_e32 v24, 0xb0, v142
	v_cvt_pk_bf16_f32 v18, v30, v35
	v_cvt_pk_bf16_f32 v20, v32, v20
	v_cvt_pk_bf16_f32 v21, v31, v21
	v_ashrrev_i32_e32 v25, 31, v24
	global_store_dwordx4 v[22:23], v[18:21], off
	s_nop 1
	v_lshlrev_b64 v[18:19], 9, v[24:25]
	v_lshl_add_u64 v[18:19], s[0:1], 0, v[18:19]
	v_lshl_add_u64 v[22:23], v[18:19], 0, v[0:1]
	global_load_dwordx4 v[18:21], v[22:23], off
	s_waitcnt vmcnt(0)
	v_lshlrev_b32_e32 v0, 16, v18
	v_fma_f32 v0, v38, v0, v14
	v_mul_f32_e32 v14, 0x3d372713, v0
	v_mul_f32_e32 v14, v0, v14
	v_fma_f32 v14, v0, v14, v0
	v_mul_f32_e32 v14, 0x3f4c422a, v14
	v_mul_f32_e64 v25, |v14|, s76
	v_add_f32_e32 v25, v25, v25
	v_exp_f32_e32 v25, v25
	s_nop 0
	v_add_f32_e32 v25, 1.0, v25
	v_rcp_f32_e32 v25, v25
	s_nop 0
	v_fma_f32 v25, v25, -2.0, 1.0
	v_lshlrev_b32_e32 v30, 16, v20
	v_fma_f32 v10, v26, v30, v10
	v_mul_f32_e32 v30, 0x3d372713, v10
	v_mul_f32_e32 v30, v10, v30
	v_fma_f32 v30, v10, v30, v10
	v_mul_f32_e32 v30, 0x3f4c422a, v30
	v_mul_f32_e64 v31, |v30|, s76
	v_add_f32_e32 v31, v31, v31
	v_exp_f32_e32 v31, v31
	s_nop 0
	v_add_f32_e32 v31, 1.0, v31
	v_rcp_f32_e32 v31, v31
	s_nop 0
	v_fma_f32 v31, v31, -2.0, 1.0
	v_and_b32_e32 v18, 0xffff0000, v18
	v_fma_f32 v18, v39, v18, v15
	v_mul_f32_e32 v15, 0x3d372713, v18
	v_mul_f32_e32 v15, v18, v15
	v_fma_f32 v15, v18, v15, v18
	v_mul_f32_e32 v15, 0x3f4c422a, v15
	v_mul_f32_e64 v32, |v15|, s76
	v_add_f32_e32 v32, v32, v32
	v_exp_f32_e32 v32, v32
	s_nop 0
	v_add_f32_e32 v32, 1.0, v32
	v_rcp_f32_e32 v32, v32
	s_nop 0
	v_fma_f32 v32, v32, -2.0, 1.0
	v_and_b32_e32 v20, 0xffff0000, v20
	v_fma_f32 v20, v27, v20, v11
	v_mul_f32_e32 v11, 0x3d372713, v20
	v_mul_f32_e32 v11, v20, v11
	v_fma_f32 v11, v20, v11, v20
	v_mul_f32_e32 v11, 0x3f4c422a, v11
	v_mul_f32_e64 v33, |v11|, s76
	v_add_f32_e32 v33, v33, v33
	v_exp_f32_e32 v33, v33
	s_nop 0
	v_add_f32_e32 v33, 1.0, v33
	v_rcp_f32_e32 v33, v33
	s_nop 0
	v_fma_f32 v33, v33, -2.0, 1.0
	v_lshlrev_b32_e32 v34, 16, v19
	v_fma_f32 v16, v40, v34, v16
	v_mul_f32_e32 v34, 0x3d372713, v16
	v_mul_f32_e32 v34, v16, v34
	v_fma_f32 v34, v16, v34, v16
	v_mul_f32_e32 v34, 0x3f4c422a, v34
	v_mul_f32_e64 v35, |v34|, s76
	v_add_f32_e32 v35, v35, v35
	v_exp_f32_e32 v35, v35
	s_nop 0
	v_add_f32_e32 v35, 1.0, v35
	v_rcp_f32_e32 v35, v35
	s_nop 0
	v_fma_f32 v35, v35, -2.0, 1.0
	v_lshlrev_b32_e32 v36, 16, v21
	v_fma_f32 v12, v28, v36, v12
	v_mul_f32_e32 v36, 0x3d372713, v12
	v_mul_f32_e32 v36, v12, v36
	v_fma_f32 v36, v12, v36, v12
	v_mul_f32_e32 v36, 0x3f4c422a, v36
	v_mul_f32_e64 v37, |v36|, s76
	v_add_f32_e32 v37, v37, v37
	v_exp_f32_e32 v37, v37
	s_nop 0
	v_add_f32_e32 v37, 1.0, v37
	v_rcp_f32_e32 v37, v37
	s_nop 0
	v_fma_f32 v37, v37, -2.0, 1.0
	v_and_b32_e32 v19, 0xffff0000, v19
	v_fmac_f32_e32 v17, v41, v19
	v_mul_f32_e32 v19, 0x3d372713, v17
	v_mul_f32_e32 v19, v17, v19
	v_fma_f32 v19, v17, v19, v17
	v_mul_f32_e32 v19, 0x3f4c422a, v19
	v_mul_f32_e64 v42, |v19|, s76
	v_add_f32_e32 v42, v42, v42
	v_exp_f32_e32 v42, v42
	s_nop 0
	v_add_f32_e32 v42, 1.0, v42
	v_rcp_f32_e32 v42, v42
	s_nop 0
	v_fma_f32 v42, v42, -2.0, 1.0
	v_and_b32_e32 v21, 0xffff0000, v21
	v_fmac_f32_e32 v13, v29, v21
	v_mul_f32_e32 v21, 0x3d372713, v13
	v_mul_f32_e32 v21, v13, v21
	v_fma_f32 v21, v13, v21, v13
	v_mul_f32_e32 v21, 0x3f4c422a, v21
	v_mul_f32_e64 v43, |v21|, s76
	v_add_f32_e32 v43, v43, v43
	v_exp_f32_e32 v43, v43
	s_nop 0
	v_add_f32_e32 v43, 1.0, v43
	v_rcp_f32_e32 v43, v43
	s_nop 0
	v_fma_f32 v43, v43, -2.0, 1.0
	v_bfi_b32 v19, s10, v42, v19
	v_mul_f32_e32 v17, 0.5, v17
	v_add_f32_e32 v19, 1.0, v19
	v_mul_f32_e32 v17, v17, v19
	v_bfi_b32 v19, s10, v37, v36
	v_mul_f32_e32 v12, 0.5, v12
	v_add_f32_e32 v19, 1.0, v19
	v_mul_f32_e32 v19, v12, v19
	v_mul_f32_e32 v12, 0.5, v20
	v_bfi_b32 v20, s10, v31, v30
	v_mul_f32_e32 v10, 0.5, v10
	v_add_f32_e32 v20, 1.0, v20
	v_mul_f32_e32 v20, v10, v20
	v_bfi_b32 v10, s10, v33, v11
	v_bfi_b32 v11, s10, v25, v14
	v_add_f32_e32 v10, 1.0, v10
	v_mul_f32_e32 v0, 0.5, v0
	v_add_f32_e32 v11, 1.0, v11
	v_mul_f32_e32 v12, v12, v10
	v_mul_f32_e32 v10, 0.5, v18
	v_mul_f32_e32 v18, v0, v11
	v_bfi_b32 v0, s10, v32, v15
	v_add_f32_e32 v0, 1.0, v0
	v_mul_f32_e32 v25, v10, v0
	v_bfi_b32 v10, s10, v43, v21
	v_mul_f32_e32 v13, 0.5, v13
	v_lshlrev_b32_e32 v0, 4, v24
	v_add_f32_e32 v10, 1.0, v10
	v_bfi_b32 v34, s10, v35, v34
	v_mul_f32_e32 v13, v13, v10
	v_or_b32_e32 v10, v0, v136
	v_mul_f32_e32 v16, 0.5, v16
	v_add_f32_e32 v34, 1.0, v34
	v_ashrrev_i32_e32 v11, 31, v10
	v_mul_f32_e32 v16, v16, v34
	v_lshlrev_b64 v[10:11], 10, v[10:11]
	v_lshl_add_u64 v[14:15], v[134:135], 0, v[10:11]
	v_cvt_pk_bf16_f32 v10, v18, v25
	v_cvt_pk_bf16_f32 v11, v16, v17
	v_cvt_pk_bf16_f32 v12, v20, v12
	v_cvt_pk_bf16_f32 v13, v19, v13
	global_store_dwordx4 v[14:15], v[10:13], off
	global_load_dwordx4 v[10:13], v[22:23], off offset:256
	s_waitcnt vmcnt(0)
	v_lshlrev_b32_e32 v14, 16, v10
	v_and_b32_e32 v15, 0xffff0000, v10
	v_pk_fma_f32 v[6:7], v[38:39], v[14:15], v[6:7]
	s_nop 0
	v_mul_f32_e32 v10, 0x3d372713, v6
	v_mul_f32_e32 v10, v6, v10
	v_fma_f32 v10, v6, v10, v6
	v_mul_f32_e32 v10, 0x3f4c422a, v10
	v_mul_f32_e64 v14, |v10|, s76
	v_add_f32_e32 v14, v14, v14
	v_exp_f32_e32 v14, v14
	s_nop 0
	v_add_f32_e32 v14, 1.0, v14
	v_rcp_f32_e32 v14, v14
	s_nop 0
	v_fma_f32 v14, v14, -2.0, 1.0
	v_lshlrev_b32_e32 v16, 16, v12
	v_and_b32_e32 v17, 0xffff0000, v12
	v_pk_fma_f32 v[2:3], v[26:27], v[16:17], v[2:3]
	s_nop 0
	v_mul_f32_e32 v12, 0x3d372713, v2
	v_mul_f32_e32 v12, v2, v12
	v_fma_f32 v12, v2, v12, v2
	v_mul_f32_e32 v12, 0x3f4c422a, v12
	v_mul_f32_e64 v15, |v12|, s76
	v_add_f32_e32 v15, v15, v15
	v_exp_f32_e32 v15, v15
	s_nop 0
	v_add_f32_e32 v15, 1.0, v15
	v_rcp_f32_e32 v15, v15
	s_nop 0
	v_fma_f32 v15, v15, -2.0, 1.0
	v_mul_f32_e32 v16, 0x3d372713, v7
	v_mul_f32_e32 v16, v7, v16
	v_fma_f32 v16, v7, v16, v7
	v_mul_f32_e32 v16, 0x3f4c422a, v16
	v_mul_f32_e64 v17, |v16|, s76
	v_add_f32_e32 v17, v17, v17
	v_exp_f32_e32 v17, v17
	s_nop 0
	v_add_f32_e32 v17, 1.0, v17
	v_rcp_f32_e32 v17, v17
	s_nop 0
	v_fma_f32 v17, v17, -2.0, 1.0
	v_mul_f32_e32 v18, 0x3d372713, v3
	v_mul_f32_e32 v18, v3, v18
	v_fma_f32 v18, v3, v18, v3
	v_mul_f32_e32 v18, 0x3f4c422a, v18
	v_mul_f32_e64 v19, |v18|, s76
	v_add_f32_e32 v19, v19, v19
	v_exp_f32_e32 v19, v19
	s_nop 0
	v_add_f32_e32 v19, 1.0, v19
	v_rcp_f32_e32 v19, v19
	s_nop 0
	v_fma_f32 v19, v19, -2.0, 1.0
	v_lshlrev_b32_e32 v20, 16, v11
	v_and_b32_e32 v21, 0xffff0000, v11
	v_pk_fma_f32 v[8:9], v[40:41], v[20:21], v[8:9]
	s_nop 0
	v_mul_f32_e32 v11, 0x3d372713, v8
	v_mul_f32_e32 v11, v8, v11
	v_fma_f32 v11, v8, v11, v8
	v_mul_f32_e32 v11, 0x3f4c422a, v11
	v_mul_f32_e64 v20, |v11|, s76
	v_add_f32_e32 v20, v20, v20
	v_exp_f32_e32 v20, v20
	s_nop 0
	v_add_f32_e32 v20, 1.0, v20
	v_rcp_f32_e32 v20, v20
	s_nop 0
	v_fma_f32 v20, v20, -2.0, 1.0
	v_lshlrev_b32_e32 v22, 16, v13
	v_and_b32_e32 v23, 0xffff0000, v13
	v_pk_fma_f32 v[4:5], v[28:29], v[22:23], v[4:5]
	s_nop 0
	v_mul_f32_e32 v13, 0x3d372713, v4
	v_mul_f32_e32 v13, v4, v13
	v_fma_f32 v13, v4, v13, v4
	v_mul_f32_e32 v13, 0x3f4c422a, v13
	v_mul_f32_e64 v21, |v13|, s76
	v_add_f32_e32 v21, v21, v21
	v_exp_f32_e32 v21, v21
	s_nop 0
	v_add_f32_e32 v21, 1.0, v21
	v_rcp_f32_e32 v21, v21
	s_nop 0
	v_fma_f32 v21, v21, -2.0, 1.0
	v_mul_f32_e32 v22, 0x3d372713, v9
	v_mul_f32_e32 v22, v9, v22
	v_fma_f32 v22, v9, v22, v9
	v_mul_f32_e32 v22, 0x3f4c422a, v22
	v_mul_f32_e64 v23, |v22|, s76
	v_add_f32_e32 v23, v23, v23
	v_exp_f32_e32 v23, v23
	s_nop 0
	v_add_f32_e32 v23, 1.0, v23
	v_rcp_f32_e32 v23, v23
	s_nop 0
	v_fma_f32 v23, v23, -2.0, 1.0
	v_mul_f32_e32 v24, 0x3d372713, v5
	v_mul_f32_e32 v24, v5, v24
	v_fma_f32 v24, v5, v24, v5
	v_mul_f32_e32 v24, 0x3f4c422a, v24
	v_cmp_nlt_f32_e64 s[0:1], |v24|, s11
	s_and_saveexec_b64 s[2:3], s[0:1]
	s_xor_b64 s[0:1], exec, s[2:3]
	s_cbranch_execz .LBB0_995
	v_add_f32_e64 v25, |v24|, |v24|
	v_mul_f32_e32 v26, 0x3fb8aa3b, v25
	v_rndne_f32_e32 v27, v26
	v_sub_f32_e32 v28, v26, v27
	v_fma_f32 v26, v25, s76, -v26
	v_fmac_f32_e32 v26, 0x32a5705f, v25
	v_add_f32_e32 v26, v28, v26
	v_cvt_i32_f32_e32 v27, v27
	v_exp_f32_e32 v26, v26
	v_cmp_ngt_f32_e32 vcc, s71, v25
	v_ldexp_f32 v26, v26, v27
	s_nop 0
	v_cndmask_b32_e32 v26, 0, v26, vcc
	v_cmp_nlt_f32_e32 vcc, s30, v25
	s_nop 1
	v_cndmask_b32_e32 v25, v186, v26, vcc
	v_add_f32_e32 v25, 1.0, v25
	v_rcp_f32_e32 v25, v25
	s_nop 0
	v_fma_f32 v25, v25, -2.0, 1.0
